# counted lgkmcnt waits: each of the 4 MFMAs after a K/V LDS read batch waits only for its own fragment (20 sites in the three attention tile loops), on top of v14
# speedup vs baseline: 1.0043x; 1.0043x over previous
; #define MFMA32(a, b, c) __builtin_amdgcn_mfma_f32_32x32x16_bf16((a), (b), (c), 0, 0, 0)
; #define LGKM0() asm volatile("s_waitcnt lgkmcnt(0)" ::: "memory")
; #define SBAR() __builtin_amdgcn_sched_barrier(0)
; #define V_ISSUE(va, b, d) do { _Pragma("unroll") for (int k4 = 0; k4 < 4; ++k4) { DS_TR16(vlo[b][k4], va, (16 * k4) * VP + (d) * 64); DS_TR16(vhi[b][k4], va, (16 * k4 + 8) * VP + (d) * 64); } } while (0)
; #define K_ISSUE(b, kb) do { DS_RD128(kfr[b][0], kaddr, (2 * (kb)) * 32); DS_RD128(kfr[b][1], kaddr, 32 * KP + (2 * (kb)) * 32); \
;                             DS_RD128(kfr[b][2], kaddr, (2 * (kb) + 1) * 32); DS_RD128(kfr[b][3], kaddr, 32 * KP + (2 * (kb) + 1) * 32); } while (0)
; template <int DQK, int DV, int MODE>
; __device__ __forceinline__ void attn_item(LAS unsigned char* lds, int item, const AttnCtx& cx) {
;     ...
;     auto do_qk = [&](int j, bool vpre) {
;         const unsigned kaddr = (unsigned)(size_t)(lds + (j % NST) * SB + koff) + r * KP + 16 * h;
;         const unsigned va = vaddr_of(j);
;         bf16x8 kfr[1][4];
;         K_ISSUE(0, 0);
; #pragma unroll
;         for (int kb = 0; kb < NQF / 2; ++kb) {
;             LGKM0(); SBAR();
;             if (kb == 0) { if (MODE == 1) { s0 = MFMA32(kfr[0][0], qf[0], cin0); s1 = MFMA32(kfr[0][1], qf[0], cin1); } else { s0 = MFMA32(kfr[0][0], qf[0], negm); s1 = MFMA32(kfr[0][1], qf[0], negm); } }
;             else { s0 = MFMA32(kfr[0][0], qf[2 * kb], s0); s1 = MFMA32(kfr[0][1], qf[2 * kb], s1); }
;             s0 = MFMA32(kfr[0][2], qf[2 * kb + 1], s0); s1 = MFMA32(kfr[0][3], qf[2 * kb + 1], s1);
;             SBAR();
;             if (kb + 1 < NQF / 2) K_ISSUE(0, kb + 1); else if (vpre) V_ISSUE(va, 0, 0);
;         }
.LBB0_243:
	s_cmp_lg_u32 s82, 0
	s_cselect_b64 s[46:47], -1, 0
	s_xor_b64 s[50:51], s[24:25], -1
	s_and_b64 s[46:47], s[50:51], s[46:47]
	s_and_b64 vcc, exec, s[46:47]
	s_cbranch_vccnz .LBB0_246
	s_and_b32 s3, s82, 3
	s_mul_i32 s3, s3, 0x9800
	s_add_i32 s3, s3, 0
	s_add_i32 s36, s3, s76
	v_add_u32_e32 v213, s36, v202
	ds_read_b128 v[98:101], v213 offset:0
	ds_read_b128 v[130:133], v213 offset:4608
	ds_read_b128 v[134:137], v213 offset:32
	ds_read_b128 v[138:141], v213 offset:4640
	s_waitcnt lgkmcnt(3)
	s_nop 0
	s_nop 0
	v_mfma_f32_32x32x16_bf16 v[82:97], v[98:101], v[146:149], v[114:129]
	s_waitcnt lgkmcnt(2)
	v_mfma_f32_32x32x16_bf16 v[98:113], v[130:133], v[146:149], v[114:129]
	s_waitcnt lgkmcnt(1)
	v_mfma_f32_32x32x16_bf16 v[82:97], v[134:137], v[150:153], v[82:97]
	s_waitcnt lgkmcnt(0)
	v_mfma_f32_32x32x16_bf16 v[98:113], v[138:141], v[150:153], v[98:113]
	ds_read_b128 v[130:133], v213 offset:64
	ds_read_b128 v[134:137], v213 offset:4672
	ds_read_b128 v[138:141], v213 offset:96
	ds_read_b128 v[142:145], v213 offset:4704
	s_waitcnt lgkmcnt(3)
	s_nop 0
	s_nop 0
	v_mfma_f32_32x32x16_bf16 v[82:97], v[130:133], v[154:157], v[82:97]
	s_waitcnt lgkmcnt(2)
	v_mfma_f32_32x32x16_bf16 v[98:113], v[134:137], v[154:157], v[98:113]
	s_waitcnt lgkmcnt(1)
	v_mfma_f32_32x32x16_bf16 v[82:97], v[138:141], v[158:161], v[82:97]
	s_waitcnt lgkmcnt(0)
	v_mfma_f32_32x32x16_bf16 v[98:113], v[142:145], v[158:161], v[98:113]
	s_andn2_b64 vcc, exec, s[24:25]
	s_cbranch_vccnz .LBB0_246
	s_addk_i32 s3, 0x4800
	v_add_u32_e32 v130, s3, v203
	ds_read_b64_tr_b16 v[162:163], v130 offset:0
	ds_read_b64_tr_b16 v[164:165], v130 offset:2560
	ds_read_b64_tr_b16 v[166:167], v130 offset:5120
	ds_read_b64_tr_b16 v[168:169], v130 offset:7680
	ds_read_b64_tr_b16 v[170:171], v130 offset:10240
	ds_read_b64_tr_b16 v[172:173], v130 offset:12800
	ds_read_b64_tr_b16 v[174:175], v130 offset:15360
	ds_read_b64_tr_b16 v[176:177], v130 offset:17920

; #define SBAR() __builtin_amdgcn_sched_barrier(0)
; template <int DQK, int DV, int MODE>
; __device__ __forceinline__ void attn_item(LAS unsigned char* lds, int item, const AttnCtx& cx) {
;     ...
;     auto do_qk = [&](int j, bool vpre) {
;         const unsigned kaddr = (unsigned)(size_t)(lds + (j % NST) * SB + koff) + r * KP + 16 * h;
;         const unsigned va = vaddr_of(j);
;         bf16x8 kfr[1][4];
;         K_ISSUE(0, 0);
; #pragma unroll
;         for (int kb = 0; kb < NQF / 2; ++kb) {
;             LGKM0(); SBAR();
;             if (kb == 0) { if (MODE == 1) { s0 = MFMA32(kfr[0][0], qf[0], cin0); s1 = MFMA32(kfr[0][1], qf[0], cin1); } else { s0 = MFMA32(kfr[0][0], qf[0], negm); s1 = MFMA32(kfr[0][1], qf[0], negm); } }
;             else { s0 = MFMA32(kfr[0][0], qf[2 * kb], s0); s1 = MFMA32(kfr[0][1], qf[2 * kb], s1); }
;             s0 = MFMA32(kfr[0][2], qf[2 * kb + 1], s0); s1 = MFMA32(kfr[0][3], qf[2 * kb + 1], s1);
;             SBAR();
;             if (kb + 1 < NQF / 2) K_ISSUE(0, kb + 1); else if (vpre) V_ISSUE(va, 0, 0);
;         }
;     ...
;         for (int i = 0; i < 16; ++i) { s0[i] = fast_exp2(s0[i]); s1[i] = fast_exp2(s1[i]); }
;         u32x4 w;
;         w.x = pk2(s0[0], s0[1]); w.y = pk2(s0[2], s0[3]); w.z = pk2(s0[4], s0[5]); w.w = pk2(s0[6], s0[7]); pa[0][0] = __builtin_bit_cast(bf16x8, w);
;         w.x = pk2(s0[8], s0[9]); w.y = pk2(s0[10], s0[11]); w.z = pk2(s0[12], s0[13]); w.w = pk2(s0[14], s0[15]); pa[0][1] = __builtin_bit_cast(bf16x8, w);
;         w.x = pk2(s1[0], s1[1]); w.y = pk2(s1[2], s1[3]); w.z = pk2(s1[4], s1[5]); w.w = pk2(s1[6], s1[7]); pa[1][0] = __builtin_bit_cast(bf16x8, w);
;         w.x = pk2(s1[8], s1[9]); w.y = pk2(s1[10], s1[11]); w.z = pk2(s1[12], s1[13]); w.w = pk2(s1[14], s1[15]); pa[1][1] = __builtin_bit_cast(bf16x8, w);
;     };
;     auto do_pv = [&](unsigned va) {
; #pragma unroll
;         for (int k4 = 0; k4 < 4; ++k4) Lacc = MFMA32(ones8, pa[k4 >> 1][k4 & 1], Lacc);
; #pragma unroll
;         for (int d = 0; d < NDV; ++d) {
;             LGKM0(); SBAR();
; #pragma unroll
;             for (int k4 = 0; k4 < 4; ++k4) {
;                 const bf16x8 vf = __builtin_shufflevector(vlo[d & 1][k4], vhi[d & 1][k4], 0, 1, 2, 3, 4, 5, 6, 7);
;                 O[d] = MFMA32(vf, pa[k4 >> 1][k4 & 1], O[d]);
;             }
;             SBAR();
;             if (d + 1 < NDV) V_ISSUE(va, (d + 1) & 1, d + 1);
.LBB0_257:
	s_mov_b32 s90, s88
	s_mov_b32 s91, s88
	s_mov_b32 s89, s88
	v_mov_b64_e32 v[228:229], s[90:91]
	v_exp_f32_e32 v82, v82
	v_exp_f32_e32 v83, v83
	v_exp_f32_e32 v84, v84
	v_exp_f32_e32 v85, v85
	v_exp_f32_e32 v86, v86
	v_exp_f32_e32 v87, v87
	v_exp_f32_e32 v88, v88
	v_exp_f32_e32 v89, v89
	v_mov_b64_e32 v[226:227], s[88:89]
	v_cvt_pk_bf16_f32 v230, v82, v83
	v_cvt_pk_bf16_f32 v231, v84, v85
	v_cvt_pk_bf16_f32 v232, v86, v87
	v_cvt_pk_bf16_f32 v233, v88, v89
	v_exp_f32_e32 v90, v90
	v_exp_f32_e32 v91, v91
	v_mfma_f32_32x32x16_bf16 v[66:81], v[226:229], v[230:233], v[66:81]
	v_exp_f32_e32 v92, v92
	v_exp_f32_e32 v93, v93
	v_exp_f32_e32 v94, v94
	v_exp_f32_e32 v95, v95
	v_exp_f32_e32 v96, v96
	v_exp_f32_e32 v97, v97
	v_cvt_pk_bf16_f32 v234, v90, v91
	v_cvt_pk_bf16_f32 v235, v92, v93
	v_cvt_pk_bf16_f32 v236, v94, v95
	v_cvt_pk_bf16_f32 v237, v96, v97
	v_exp_f32_e32 v98, v98
	v_exp_f32_e32 v99, v99
	v_mfma_f32_32x32x16_bf16 v[66:81], v[226:229], v[234:237], v[66:81]
	v_exp_f32_e32 v100, v100
	v_exp_f32_e32 v101, v101
	v_exp_f32_e32 v102, v102
	v_exp_f32_e32 v103, v103
	v_exp_f32_e32 v104, v104
	v_exp_f32_e32 v105, v105
	v_cvt_pk_bf16_f32 v238, v98, v99
	v_cvt_pk_bf16_f32 v239, v100, v101
	v_cvt_pk_bf16_f32 v240, v102, v103
	v_cvt_pk_bf16_f32 v241, v104, v105
	v_exp_f32_e32 v106, v106
	v_exp_f32_e32 v107, v107
	v_mfma_f32_32x32x16_bf16 v[66:81], v[226:229], v[238:241], v[66:81]
	v_exp_f32_e32 v108, v108
	v_exp_f32_e32 v109, v109
	v_exp_f32_e32 v110, v110
	v_exp_f32_e32 v111, v111
	v_exp_f32_e32 v112, v112
	v_exp_f32_e32 v113, v113
	v_cvt_pk_bf16_f32 v242, v106, v107
	v_cvt_pk_bf16_f32 v243, v108, v109
	v_cvt_pk_bf16_f32 v244, v110, v111
	v_cvt_pk_bf16_f32 v245, v112, v113
	s_and_b32 s3, s82, 3
	s_mul_i32 s3, s3, 0x9800
	v_mfma_f32_32x32x16_bf16 v[66:81], v[226:229], v[242:245], v[66:81]
	s_waitcnt lgkmcnt(0)
	s_add_i32 s3, s3, 0
	s_addk_i32 s3, 0x4800
	v_add_u32_e32 v213, s3, v203
	v_mfma_f32_32x32x16_bf16 v[50:65], v[162:165], v[230:233], v[50:65]
	v_mfma_f32_32x32x16_bf16 v[50:65], v[166:169], v[234:237], v[50:65]
	v_mfma_f32_32x32x16_bf16 v[50:65], v[170:173], v[238:241], v[50:65]
	v_mfma_f32_32x32x16_bf16 v[50:65], v[174:177], v[242:245], v[50:65]
	ds_read_b64_tr_b16 v[162:163], v213 offset:64
	ds_read_b64_tr_b16 v[164:165], v213 offset:2624
	ds_read_b64_tr_b16 v[166:167], v213 offset:5184
	ds_read_b64_tr_b16 v[168:169], v213 offset:7744
	ds_read_b64_tr_b16 v[170:171], v213 offset:10304
	ds_read_b64_tr_b16 v[172:173], v213 offset:12864
	ds_read_b64_tr_b16 v[174:175], v213 offset:15424
	ds_read_b64_tr_b16 v[176:177], v213 offset:17984
	s_waitcnt lgkmcnt(6)
	s_nop 0
	s_nop 0
	v_mfma_f32_32x32x16_bf16 v[34:49], v[162:165], v[230:233], v[34:49]
	s_waitcnt lgkmcnt(4)
	v_mfma_f32_32x32x16_bf16 v[34:49], v[166:169], v[234:237], v[34:49]
	s_waitcnt lgkmcnt(2)
	v_mfma_f32_32x32x16_bf16 v[34:49], v[170:173], v[238:241], v[34:49]
	s_waitcnt lgkmcnt(0)
	v_mfma_f32_32x32x16_bf16 v[34:49], v[174:177], v[242:245], v[34:49]
	ds_read_b64_tr_b16 v[162:163], v213 offset:128
	ds_read_b64_tr_b16 v[164:165], v213 offset:2688
	ds_read_b64_tr_b16 v[166:167], v213 offset:5248
	ds_read_b64_tr_b16 v[168:169], v213 offset:7808
	ds_read_b64_tr_b16 v[170:171], v213 offset:10368
	ds_read_b64_tr_b16 v[172:173], v213 offset:12928
	ds_read_b64_tr_b16 v[174:175], v213 offset:15488
	ds_read_b64_tr_b16 v[176:177], v213 offset:18048
	s_waitcnt lgkmcnt(6)
	s_nop 0
	s_nop 0
	v_mfma_f32_32x32x16_bf16 v[18:33], v[162:165], v[230:233], v[18:33]
	s_waitcnt lgkmcnt(4)
	v_mfma_f32_32x32x16_bf16 v[18:33], v[166:169], v[234:237], v[18:33]
	s_waitcnt lgkmcnt(2)
	v_mfma_f32_32x32x16_bf16 v[18:33], v[170:173], v[238:241], v[18:33]
	s_waitcnt lgkmcnt(0)
	v_mfma_f32_32x32x16_bf16 v[18:33], v[174:177], v[242:245], v[18:33]
	ds_read_b64_tr_b16 v[226:227], v213 offset:192
	ds_read_b64_tr_b16 v[228:229], v213 offset:2752
	ds_read_b64_tr_b16 v[246:247], v213 offset:5312
	ds_read_b64_tr_b16 v[248:249], v213 offset:7872
	ds_read_b64_tr_b16 v[222:223], v213 offset:10432
	ds_read_b64_tr_b16 v[224:225], v213 offset:12992
	ds_read_b64_tr_b16 v[214:215], v213 offset:15552
	ds_read_b64_tr_b16 v[216:217], v213 offset:18112
	s_waitcnt lgkmcnt(6)
	s_nop 0
	s_nop 0
	v_mfma_f32_32x32x16_bf16 v[2:17], v[226:229], v[230:233], v[2:17]
	s_waitcnt lgkmcnt(4)
	v_mfma_f32_32x32x16_bf16 v[2:17], v[246:249], v[234:237], v[2:17]
	s_waitcnt lgkmcnt(2)
	v_mfma_f32_32x32x16_bf16 v[2:17], v[222:225], v[238:241], v[2:17]
	s_waitcnt lgkmcnt(0)
	v_mfma_f32_32x32x16_bf16 v[2:17], v[214:217], v[242:245], v[2:17]
	s_add_i32 s82, s82, 1
	s_cmp_ge_u32 s82, s83
	s_cselect_b64 s[50:51], -1, 0
	s_or_b64 s[50:51], s[24:25], s[50:51]
	s_and_b64 vcc, exec, s[50:51]
	s_cbranch_vccnz .LBB0_200
	s_and_b32 s3, s82, 3
	s_mul_i32 s3, s3, 0x9800
	s_add_i32 s3, s77, s3
	v_add_u32_e32 v213, s3, v202
	ds_read_b128 v[98:101], v213 offset:0
	ds_read_b128 v[102:105], v213 offset:4608
	ds_read_b128 v[106:109], v213 offset:32
	ds_read_b128 v[110:113], v213 offset:4640
	s_waitcnt lgkmcnt(3)
	s_nop 0
	s_nop 0
	v_mfma_f32_32x32x16_bf16 v[82:97], v[98:101], v[146:149], v[130:145]
	s_waitcnt lgkmcnt(2)
	v_mfma_f32_32x32x16_bf16 v[130:145], v[102:105], v[146:149], v[130:145]
	s_waitcnt lgkmcnt(1)
	v_mfma_f32_32x32x16_bf16 v[82:97], v[106:109], v[150:153], v[82:97]
	s_waitcnt lgkmcnt(0)
	v_mfma_f32_32x32x16_bf16 v[130:145], v[110:113], v[150:153], v[130:145]
	ds_read_b128 v[98:101], v213 offset:64
	ds_read_b128 v[102:105], v213 offset:4672
	ds_read_b128 v[106:109], v213 offset:96
	ds_read_b128 v[110:113], v213 offset:4704
	s_waitcnt lgkmcnt(3)
	s_nop 0
	s_nop 0
	v_mfma_f32_32x32x16_bf16 v[82:97], v[98:101], v[154:157], v[82:97]
	s_waitcnt lgkmcnt(2)
	v_mfma_f32_32x32x16_bf16 v[130:145], v[102:105], v[154:157], v[130:145]
	s_waitcnt lgkmcnt(1)
	v_mfma_f32_32x32x16_bf16 v[82:97], v[106:109], v[158:161], v[82:97]
	s_waitcnt lgkmcnt(0)
	v_mfma_f32_32x32x16_bf16 v[130:145], v[110:113], v[158:161], v[130:145]
	s_nop 11
	v_mov_b32_e32 v98, v130
	v_mov_b32_e32 v99, v131
	v_mov_b32_e32 v100, v132
	v_mov_b32_e32 v101, v133
	v_mov_b32_e32 v102, v134
	v_mov_b32_e32 v103, v135
	v_mov_b32_e32 v104, v136
	v_mov_b32_e32 v105, v137
	v_mov_b32_e32 v106, v138
	v_mov_b32_e32 v107, v139
	v_mov_b32_e32 v108, v140
	v_mov_b32_e32 v109, v141
	v_mov_b32_e32 v110, v142
	v_mov_b32_e32 v111, v143
	v_mov_b32_e32 v112, v144
	v_mov_b32_e32 v113, v145
	s_branch .LBB0_200

; template <int DQK, int DV, int MODE>
; __device__ __forceinline__ void attn_item(LAS unsigned char* lds, int item, const AttnCtx& cx) {
;     ...
;         const int unit = item * 2 + hf, nbk = cx.n >> 7; head = unit / nbk; const int blk = unit - head * nbk; tok0 = blk * 128; S = seq_len_of(cx.row0 + tok0); seqbase = ((cx.row0 + tok0) & ~(S - 1)) - cx.row0;
;         qcol = COL_C_Q + head * 128; kcol = COL_C_K + head * 128; vcol = COL_C_V + head * 128; ntiles = 4;
;         c_dlog = 2 * (head >> 2); const int b = (tok0 - seqbase) >> 7; c_rho = b & ((1 << c_dlog) - 1); c_l0 = (b >> c_dlog) * 128; c_L = S >> c_dlog;
;         c_lq = c_l0 + 32 * wq + r; qtok = seqbase + (c_lq << c_dlog) + c_rho;
;     }
;     auto ktok = [&](int j, int kr) -> int {
;         if (MODE == 0) return seqbase + 64 * j + kr;
;         if (MODE == 1) return seqbase + min(na_rs0 + j, na_rows - 1) * 64 + kr;
;         const int lk = min(max(c_l0 - 64 + 64 * j + kr, 0), c_L - 1); return seqbase + (lk << c_dlog) + c_rho;
;     };
;     ...
;     auto gload = [&](int j) {
; #pragma unroll
;         for (int i = 0; i < NKP; ++i) { const int pid = th + 256 * i, row = pid / KPR, cp = pid % KPR; kreg[DMA ? 0 : i] = *(const u32x4*)(P + (size_t)ktok(j, row) * NIN + kcol + cp * 8); }
;         if (loadV) {
; #pragma unroll
;             for (int i = 0; i < NVP; ++i) { const int pid = th + 256 * i, row = pid / VPR, cp = pid % VPR; vreg[DMA ? 0 : i] = *(const u32x4*)(P + (size_t)ktok(j, row) * NIN + vcol + cp * 8); }
;         }
;     };
;     auto lstore = [&](int b) {
;         LAS unsigned char* base = lds + b * SB;
; #pragma unroll
;         for (int i = 0; i < NKP; ++i) { const int pid = th + 256 * i, row = pid / KPR, cp = pid % KPR; *(LAS u32x4*)(base + koff + row * KP + cp * 16) = kreg[DMA ? 0 : i]; }
;         if (loadV) {
; #pragma unroll
;             for (int i = 0; i < NVP; ++i) { const int pid = th + 256 * i, row = pid / VPR, cp = pid % VPR; *(LAS u32x4*)(base + voff + row * VP + cp * 16) = vreg[DMA ? 0 : i]; }
;         }
;     };
;     LAS float* biasL = (LAS float*)(lds + NST * SB) + hf * 640;
;     if (DMA) {
; #pragma unroll
;         for (int j0 = 0; j0 < DIST; ++j0) if (j0 < ntiles) issue(j0);
;     } else gload(0);
;     bf16x8 qf[NQF];
; #pragma unroll
;     for (int ks = 0; ks < NQF; ++ks) qf[ks] = *(const bf16x8*)(P + (size_t)qtok * NIN + qcol + 16 * ks + 8 * h);
.LBB0_294:
	v_mov_b32_e32 v116, v251
	v_readlane_b32 s5, v255, 24
	v_readfirstlane_b32 s0, v116
	s_ashr_i32 s43, s0, 6
	s_ashr_i32 s52, s0, 8
	s_lshl_b32 s0, s63, 1
	s_add_i32 s0, s52, s0
	s_abs_i32 s22, s0
	s_mul_hi_u32 s23, s22, s62
	s_mul_i32 s24, s23, s48
	s_sub_i32 s22, s22, s24
	s_and_b32 s1, s43, 3
	s_ashr_i32 s3, s0, 31
	s_add_i32 s24, s23, 1
	s_sub_i32 s25, s22, s48
	s_cmp_ge_u32 s22, s48
	s_cselect_b32 s23, s24, s23
	s_cselect_b32 s22, s25, s22
	s_add_i32 s24, s23, 1
	s_cmp_ge_u32 s22, s48
	s_cselect_b32 s22, s24, s23
	s_xor_b32 s22, s22, s3
	s_sub_i32 s42, s22, s3
	s_lshl_b32 s3, s42, s37
	s_sub_i32 s0, s0, s3
	s_lshl_b32 s0, s0, 7
	s_add_i32 s3, s0, s5
	s_cmpk_lt_i32 s3, 0x4000
	s_movk_i32 s4, 0xf000
	s_cselect_b32 s22, s4, 0xfffff800
	s_movk_i32 s4, 0x1000
	s_cselect_b32 s23, s4, 0x800
	s_and_b32 s3, s22, s3
	s_sub_i32 s3, s3, s5
	s_ashr_i32 s25, s42, 1
	s_and_b32 s64, s25, -2
	s_sub_i32 s0, s0, s3
	s_ashr_i32 s0, s0, 7
	s_lshl_b32 s25, -1, s64
	s_andn2_b32 s65, s0, s25
	s_ashr_i32 s0, s0, s64
	s_lshl_b32 s67, s0, 7
	s_lshl_b32 s30, s1, 5
	v_and_b32_e32 v228, 31, v116
	s_or_b32 s66, s67, s30
	v_or_b32_e32 v0, s66, v228
	v_bfe_u32 v41, v116, 4, 4
	v_lshlrev_b32_e32 v2, s64, v0
	s_add_i32 s65, s65, s3
	s_sub_i32 s0, s67, 64
	v_or_b32_e32 v229, s67, v41
	s_lshr_b32 s68, s23, s64
	v_add_u32_e32 v227, s65, v2
	v_lshrrev_b32_e32 v20, 4, v116
	v_or_b32_e32 v2, s0, v41
	v_subrev_u32_e32 v10, 32, v229
	v_max_i32_e32 v2, 0, v2
	s_add_i32 s69, s68, -1
	v_max_i32_e32 v10, 0, v10
	v_or_b32_e32 v20, -16, v20
	s_lshl_b32 s22, s42, 7
	v_min_i32_e32 v2, s69, v2
	v_subrev_u32_e32 v6, 48, v229
	v_min_i32_e32 v10, s69, v10
	v_add_u32_e32 v20, s67, v20
	s_add_i32 s24, s22, 0x1200
	s_add_i32 s38, s22, 0x1800
	v_lshlrev_b32_e32 v2, s64, v2
	v_max_i32_e32 v6, 0, v6
	v_lshlrev_b32_e32 v10, s64, v10
	v_max_i32_e32 v20, 0, v20
	v_add_u32_e32 v2, s65, v2
	v_mov_b64_e32 v[34:35], s[86:87]
	s_ashr_i32 s25, s24, 31
	v_min_i32_e32 v6, s69, v6
	v_add_u32_e32 v10, s65, v10
	v_min_i32_e32 v20, s69, v20
	s_ashr_i32 s39, s38, 31
	v_and_b32_e32 v117, 15, v116
	v_mad_i64_i32 v[14:15], s[40:41], v2, s33, v[34:35]
	s_lshl_b64 s[44:45], s[24:25], 1
	v_lshlrev_b32_e32 v6, s64, v6
	v_mad_i64_i32 v[18:19], s[24:25], v10, s33, v[34:35]
	v_lshlrev_b32_e32 v20, s64, v20
	s_lshl_b64 s[46:47], s[38:39], 1
	v_lshl_add_u64 v[2:3], v[14:15], 0, s[44:45]
	v_lshlrev_b32_e32 v212, 4, v117
	v_mov_b32_e32 v213, v1
	v_add_u32_e32 v6, s65, v6
	v_lshl_add_u64 v[10:11], v[18:19], 0, s[44:45]
	v_add_u32_e32 v20, s65, v20
	v_lshl_add_u64 v[14:15], v[14:15], 0, s[46:47]
	v_mad_i64_i32 v[16:17], s[24:25], v6, s33, v[34:35]
	v_lshl_add_u64 v[10:11], v[10:11], 0, v[212:213]
	v_mad_i64_i32 v[36:37], s[24:25], v20, s33, v[34:35]
	v_lshl_add_u64 v[14:15], v[14:15], 0, v[212:213]
	global_load_dwordx4 v[10:13], v[10:11], off
	v_lshl_add_u64 v[20:21], v[36:37], 0, s[44:45]
	global_load_dwordx4 v[30:33], v[14:15], off
	v_lshl_add_u64 v[14:15], v[16:17], 0, s[46:47]
	v_lshl_add_u64 v[20:21], v[20:21], 0, v[212:213]
	v_lshl_add_u64 v[14:15], v[14:15], 0, v[212:213]
	global_load_dwordx4 v[22:25], v[20:21], off
	global_load_dwordx4 v[26:29], v[14:15], off
	v_lshl_add_u64 v[14:15], v[18:19], 0, s[46:47]
	v_lshl_add_u64 v[14:15], v[14:15], 0, v[212:213]
	v_bfe_u32 v40, v116, 5, 1
	global_load_dwordx4 v[18:21], v[14:15], off
	v_lshl_add_u64 v[14:15], v[36:37], 0, s[46:47]
	v_mad_i64_i32 v[36:37], s[24:25], v227, s33, v[34:35]
	s_ashr_i32 s23, s22, 31
	v_lshl_add_u64 v[36:37], s[22:23], 1, v[36:37]
	v_lshlrev_b32_e32 v214, 4, v40
	v_mov_b32_e32 v215, v1
	v_lshl_add_u64 v[36:37], v[36:37], 0, v[214:215]
	s_mov_b64 s[24:25], 0x1800
	v_lshl_add_u64 v[6:7], v[16:17], 0, s[44:45]
	v_lshl_add_u64 v[38:39], v[36:37], 0, s[24:25]
	v_add_co_u32_e32 v36, vcc, s4, v36
	v_lshl_add_u64 v[2:3], v[2:3], 0, v[212:213]
	v_lshl_add_u64 v[6:7], v[6:7], 0, v[212:213]
	v_lshl_add_u64 v[14:15], v[14:15], 0, v[212:213]
	v_addc_co_u32_e32 v37, vcc, 0, v37, vcc
	global_load_dwordx4 v[2:5], v[2:3], off
	s_mul_i32 s52, s52, 0x9400
	global_load_dwordx4 v[6:9], v[6:7], off
	s_add_i32 s70, s52, 0
	global_load_dwordx4 v[14:17], v[14:15], off
	s_nop 0
	global_load_dwordx4 v[144:147], v[36:37], off offset:2048
	global_load_dwordx4 v[148:151], v[38:39], off offset:32
	global_load_dwordx4 v[152:155], v[38:39], off offset:64
	global_load_dwordx4 v[156:159], v[38:39], off offset:96
	global_load_dwordx4 v[160:163], v[38:39], off offset:128
	global_load_dwordx4 v[164:167], v[38:39], off offset:160
	global_load_dwordx4 v[168:171], v[38:39], off offset:192
	global_load_dwordx4 v[172:175], v[38:39], off offset:224
	v_mul_u32_u24_e32 v230, 0x110, v41
	v_add3_u32 v36, s70, v230, v212
	v_max_i32_e32 v178, 0, v229
	v_min_i32_e32 v178, s69, v178
	v_lshlrev_b32_e32 v178, s64, v178
	v_add_u32_e32 v178, s65, v178
	v_mad_i64_i32 v[192:193], s[40:41], v178, s33, v[34:35]
	v_lshl_add_u64 v[176:177], v[192:193], 0, s[44:45]
	v_lshl_add_u64 v[192:193], v[192:193], 0, s[46:47]
	v_lshl_add_u64 v[176:177], v[176:177], 0, v[212:213]
	v_lshl_add_u64 v[192:193], v[192:193], 0, v[212:213]
	global_load_dwordx4 v[176:179], v[176:177], off
	global_load_dwordx4 v[192:195], v[192:193], off
	v_or_b32_e32 v182, 16, v229
	v_max_i32_e32 v182, 0, v182
	v_min_i32_e32 v182, s69, v182
	v_lshlrev_b32_e32 v182, s64, v182
	v_add_u32_e32 v182, s65, v182
	v_mad_i64_i32 v[196:197], s[40:41], v182, s33, v[34:35]
	v_lshl_add_u64 v[180:181], v[196:197], 0, s[44:45]
	v_lshl_add_u64 v[196:197], v[196:197], 0, s[46:47]
	v_lshl_add_u64 v[180:181], v[180:181], 0, v[212:213]
	v_lshl_add_u64 v[196:197], v[196:197], 0, v[212:213]
	global_load_dwordx4 v[180:183], v[180:181], off
	global_load_dwordx4 v[196:199], v[196:197], off
	v_or_b32_e32 v186, 32, v229
	v_max_i32_e32 v186, 0, v186
	v_min_i32_e32 v186, s69, v186
	v_lshlrev_b32_e32 v186, s64, v186
	v_add_u32_e32 v186, s65, v186
	v_mad_i64_i32 v[200:201], s[40:41], v186, s33, v[34:35]
	v_lshl_add_u64 v[184:185], v[200:201], 0, s[44:45]
	v_lshl_add_u64 v[200:201], v[200:201], 0, s[46:47]
	v_lshl_add_u64 v[184:185], v[184:185], 0, v[212:213]
	v_lshl_add_u64 v[200:201], v[200:201], 0, v[212:213]
	global_load_dwordx4 v[184:187], v[184:185], off
	global_load_dwordx4 v[200:203], v[200:201], off
	v_or_b32_e32 v190, 48, v229
	v_max_i32_e32 v190, 0, v190
	v_min_i32_e32 v190, s69, v190
	v_lshlrev_b32_e32 v190, s64, v190
	v_add_u32_e32 v190, s65, v190
	v_mad_i64_i32 v[204:205], s[40:41], v190, s33, v[34:35]
	v_lshl_add_u64 v[188:189], v[204:205], 0, s[44:45]
	v_lshl_add_u64 v[204:205], v[204:205], 0, s[46:47]
	v_lshl_add_u64 v[188:189], v[188:189], 0, v[212:213]
	v_lshl_add_u64 v[204:205], v[204:205], 0, v[212:213]
	global_load_dwordx4 v[188:191], v[188:189], off
	global_load_dwordx4 v[204:207], v[204:205], off
	s_waitcnt vmcnt(8)
; __device__ __forceinline__ int crow(int i, int h) { return (i & 3) + 8 * (i >> 2) + 4 * h; }
; #define MFMA32(a, b, c) __builtin_amdgcn_mfma_f32_32x32x16_bf16((a), (b), (c), 0, 0, 0)
; #define LGKM0() asm volatile("s_waitcnt lgkmcnt(0)" ::: "memory")
; #define SBAR() __builtin_amdgcn_sched_barrier(0)
; #define V_ISSUE(va, b, d) do { _Pragma("unroll") for (int k4 = 0; k4 < 4; ++k4) { DS_TR16(vlo[b][k4], va, (16 * k4) * VP + (d) * 64); DS_TR16(vhi[b][k4], va, (16 * k4 + 8) * VP + (d) * 64); } } while (0)
; template <int DQK, int DV, int MODE>
; __device__ __forceinline__ void attn_item(LAS unsigned char* lds, int item, const AttnCtx& cx) {
;     ...
;     auto do_qk = [&](int j, bool vpre) {
;         const unsigned kaddr = (unsigned)(size_t)(lds + (j % NST) * SB + koff) + r * KP + 16 * h;
;         const unsigned va = vaddr_of(j);
;         bf16x8 kfr[1][4];
;         K_ISSUE(0, 0);
; #pragma unroll
;         for (int kb = 0; kb < NQF / 2; ++kb) {
;             LGKM0(); SBAR();
;             if (kb == 0) { if (MODE == 1) { s0 = MFMA32(kfr[0][0], qf[0], cin0); s1 = MFMA32(kfr[0][1], qf[0], cin1); } else { s0 = MFMA32(kfr[0][0], qf[0], negm); s1 = MFMA32(kfr[0][1], qf[0], negm); } }
;             else { s0 = MFMA32(kfr[0][0], qf[2 * kb], s0); s1 = MFMA32(kfr[0][1], qf[2 * kb], s1); }
;             s0 = MFMA32(kfr[0][2], qf[2 * kb + 1], s0); s1 = MFMA32(kfr[0][3], qf[2 * kb + 1], s1);
;             SBAR();
;             if (kb + 1 < NQF / 2) K_ISSUE(0, kb + 1); else if (vpre) V_ISSUE(va, 0, 0);
;         }
;     };
;     auto do_soft = [&](int j) {
;         if (MODE == 1) {
;             const int rk = na_rs0 + j; const int bbase = (rk - na_rq + 7) * 31 + 15 - na_cq + 64;
; #pragma unroll
;             for (int i = 0; i < 16; ++i) { s0[i] += biasL[bbase + crow(i, h)]; s1[i] += biasL[bbase + crow(i, h) + 32]; }
;         }
;         if (MODE == 2) {
;             const int lk0 = c_l0 - 64 + 64 * j;
; #pragma unroll
;             for (int i = 0; i < 16; ++i) {
;                 const int lka = lk0 + crow(i, h), lkb = lka + 32;
;                 const bool v0 = (lka >= 0) && (lka < c_L) && (abs(lka - c_lq) <= 64), v1 = (lkb >= 0) && (lkb < c_L) && (abs(lkb - c_lq) <= 64);
;                 s0[i] = v0 ? s0[i] : NEGBIG; s1[i] = v1 ? s1[i] : NEGBIG;
;             }
;         }
	ds_write_b128 v36, v[2:5]
	v_mov_b32_e32 v2, 0x1100
	s_movk_i32 s4, 0x110
	v_mad_u32_u24 v231, v41, s4, v2
	v_add3_u32 v2, s70, v231, v212
	ds_write_b128 v2, v[6:9]
	v_mov_b32_e32 v2, 0x2200
	v_mad_u32_u24 v232, v41, s4, v2
	v_add3_u32 v2, s70, v232, v212
	ds_write_b128 v2, v[10:13]
	v_mov_b32_e32 v2, 0x3300
	v_mad_u32_u24 v233, v41, s4, v2
	v_add3_u32 v2, s70, v233, v212
	v_mul_u32_u24_e32 v234, 0x140, v41
	ds_write_b128 v2, v[22:25]
	v_add3_u32 v2, s70, v234, v212
	ds_write_b128 v2, v[30:33] offset:17408
	v_mov_b32_e32 v2, 0x1400
	s_movk_i32 s3, 0x140
	v_mad_u32_u24 v235, v41, s3, v2
	v_add3_u32 v2, s70, v235, v212
	ds_write_b128 v2, v[26:29] offset:17408
	v_mov_b32_e32 v2, 0x2800
	v_mad_u32_u24 v236, v41, s3, v2
	v_add3_u32 v2, s70, v236, v212
	ds_write_b128 v2, v[18:21] offset:17408
	v_mov_b32_e32 v2, 0x3c00
	v_mad_u32_u24 v237, v41, s3, v2
	v_add3_u32 v2, s70, v237, v212
	ds_write_b128 v2, v[14:17] offset:17408
	v_lshrrev_b32_e32 v2, 2, v116
	v_lshlrev_b32_e32 v118, 2, v40
	v_and_or_b32 v2, v2, 3, v118
	v_lshlrev_b32_e32 v215, 3, v116
	v_lshlrev_b32_e32 v4, 1, v116
	v_mul_u32_u24_e32 v2, 0x140, v2
	v_and_b32_e32 v3, 24, v215
	v_and_b32_e32 v4, 32, v4
	v_or3_b32 v239, v3, v4, v2
	s_waitcnt lgkmcnt(0)
	s_barrier
	s_cmp_gt_u32 s1, 1
	s_cselect_b64 s[24:25], -1, 0
	v_mad_u32_u24 v238, v228, s4, v214
	s_mov_b32 s71, 0
	s_and_b64 vcc, exec, s[24:25]
	s_cbranch_vccnz .LBB0_297
	s_cmpk_lt_i32 s0, 0xffc1
	s_cselect_b64 s[38:39], -1, 0
	s_cmp_ge_i32 s0, s68
	s_cselect_b64 s[40:41], -1, 0
	s_or_b64 s[38:39], s[38:39], s[40:41]
	s_and_b64 vcc, exec, s[38:39]
	s_cbranch_vccnz .LBB0_298
	v_add_u32_e32 v50, s70, v238
	ds_read_b128 v[2:5], v50 offset:0
	ds_read_b128 v[6:9], v50 offset:8704
	ds_read_b128 v[34:37], v50 offset:32
	ds_read_b128 v[38:41], v50 offset:8736
	s_waitcnt lgkmcnt(0)
	s_add_i32 s1, s70, 0x4400
	v_add_u32_e32 v119, s1, v239
	v_mfma_f32_32x32x16_bf16 v[18:33], v[2:5], v[144:147], 0
	v_mfma_f32_32x32x16_bf16 v[2:17], v[6:9], v[144:147], 0
	v_mfma_f32_32x32x16_bf16 v[18:33], v[34:37], v[148:151], v[18:33]
	v_mfma_f32_32x32x16_bf16 v[2:17], v[38:41], v[148:151], v[2:17]
	ds_read_b128 v[34:37], v50 offset:64
	ds_read_b128 v[38:41], v50 offset:8768
	ds_read_b128 v[42:45], v50 offset:96
	ds_read_b128 v[46:49], v50 offset:8800
	s_waitcnt lgkmcnt(3)
	s_nop 0
	s_nop 0
	v_mfma_f32_32x32x16_bf16 v[18:33], v[34:37], v[152:155], v[18:33]
	s_waitcnt lgkmcnt(2)
	v_mfma_f32_32x32x16_bf16 v[2:17], v[38:41], v[152:155], v[2:17]
	s_waitcnt lgkmcnt(1)
	v_mfma_f32_32x32x16_bf16 v[18:33], v[42:45], v[156:159], v[18:33]
	s_waitcnt lgkmcnt(0)
	v_mfma_f32_32x32x16_bf16 v[2:17], v[46:49], v[156:159], v[2:17]
	ds_read_b128 v[34:37], v50 offset:128
	ds_read_b128 v[38:41], v50 offset:8832
	ds_read_b128 v[42:45], v50 offset:160
	ds_read_b128 v[46:49], v50 offset:8864
	s_waitcnt lgkmcnt(3)
	s_nop 0
	s_nop 0
	v_mfma_f32_32x32x16_bf16 v[18:33], v[34:37], v[160:163], v[18:33]
	s_waitcnt lgkmcnt(2)
	v_mfma_f32_32x32x16_bf16 v[2:17], v[38:41], v[160:163], v[2:17]
	s_waitcnt lgkmcnt(1)
	v_mfma_f32_32x32x16_bf16 v[18:33], v[42:45], v[164:167], v[18:33]
	s_waitcnt lgkmcnt(0)
	v_mfma_f32_32x32x16_bf16 v[2:17], v[46:49], v[164:167], v[2:17]
	ds_read_b128 v[34:37], v50 offset:192
	ds_read_b128 v[38:41], v50 offset:8896
	ds_read_b128 v[42:45], v50 offset:224
	ds_read_b128 v[46:49], v50 offset:8928
	s_waitcnt lgkmcnt(3)
	s_nop 0
	s_nop 0
	v_mfma_f32_32x32x16_bf16 v[18:33], v[34:37], v[168:171], v[18:33]
	s_waitcnt lgkmcnt(2)
	v_mfma_f32_32x32x16_bf16 v[2:17], v[38:41], v[168:171], v[2:17]
	s_waitcnt lgkmcnt(1)
	v_mfma_f32_32x32x16_bf16 v[18:33], v[42:45], v[172:175], v[18:33]
	s_waitcnt lgkmcnt(0)
	v_mfma_f32_32x32x16_bf16 v[2:17], v[46:49], v[172:175], v[2:17]
	v_or_b32_e32 v50, s0, v118
	v_sub_u32_e32 v52, v50, v0
	s_cmp_gt_i32 s0, -1
	v_sub_u32_e32 v53, 0, v52
	s_cselect_b64 s[54:55], -1, 0
	v_cmp_gt_i32_e32 vcc, s68, v50
	v_max_i32_e32 v52, v52, v53
	v_or_b32_e32 v51, 32, v50
	v_cmp_gt_u32_e64 s[0:1], s20, v52
	s_and_b64 s[38:39], s[54:55], vcc
	s_and_b64 vcc, s[38:39], s[0:1]
	v_cmp_gt_i32_e64 s[38:39], s68, v51
	v_sub_u32_e32 v51, v51, v0
	v_sub_u32_e32 v52, 0, v51
	v_max_i32_e32 v51, v51, v52
	v_or_b32_e32 v52, 1, v50
	v_cmp_lt_i32_e64 s[0:1], s21, v50
	v_cndmask_b32_e32 v18, v220, v18, vcc
	v_cmp_gt_i32_e32 vcc, s68, v52
	v_sub_u32_e32 v52, v52, v0
	v_cmp_gt_u32_e64 s[40:41], s20, v51
	s_and_b64 s[0:1], s[0:1], s[38:39]
	v_sub_u32_e32 v53, 0, v52
	s_and_b64 s[0:1], s[0:1], s[40:41]
	v_max_i32_e32 v52, v52, v53
	v_cndmask_b32_e64 v2, v220, v2, s[0:1]
	v_or_b32_e32 v51, 33, v50
	v_cmp_gt_u32_e64 s[0:1], s20, v52
	s_and_b64 s[38:39], s[54:55], vcc
	s_and_b64 vcc, s[38:39], s[0:1]
	v_cmp_gt_i32_e64 s[38:39], s68, v51
	v_sub_u32_e32 v51, v51, v0
	v_sub_u32_e32 v52, 0, v51
	v_max_i32_e32 v51, v51, v52
	s_movk_i32 s0, 0xffde
	v_cmp_gt_u32_e64 s[40:41], s20, v51
	v_or_b32_e32 v51, 2, v50
	v_cmp_lt_i32_e64 s[0:1], s0, v50
	v_sub_u32_e32 v53, v51, v0
	s_and_b64 s[0:1], s[0:1], s[38:39]
	v_sub_u32_e32 v54, 0, v53
	s_and_b64 s[0:1], s[0:1], s[40:41]
	v_cndmask_b32_e32 v19, v220, v19, vcc
	v_cmp_gt_i32_e32 vcc, s68, v51
	v_max_i32_e32 v53, v53, v54
	v_cndmask_b32_e64 v3, v220, v3, s[0:1]
	v_or_b32_e32 v52, 34, v50
	v_cmp_gt_u32_e64 s[0:1], s20, v53
	s_and_b64 s[38:39], s[54:55], vcc
	s_and_b64 vcc, s[38:39], s[0:1]
	v_cmp_lt_i32_e64 s[0:1], s21, v51
	v_sub_u32_e32 v51, v52, v0
	v_cmp_gt_i32_e64 s[38:39], s68, v52
	v_sub_u32_e32 v52, 0, v51
	v_max_i32_e32 v51, v51, v52
	v_cmp_gt_u32_e64 s[40:41], s20, v51
	v_or_b32_e32 v51, 3, v50
	v_sub_u32_e32 v53, v51, v0
	s_and_b64 s[0:1], s[0:1], s[38:39]
	v_sub_u32_e32 v54, 0, v53
	s_and_b64 s[0:1], s[0:1], s[40:41]
; __device__ __forceinline__ int crow(int i, int h) { return (i & 3) + 8 * (i >> 2) + 4 * h; }
; template <int DQK, int DV, int MODE>
; __device__ __forceinline__ void attn_item(LAS unsigned char* lds, int item, const AttnCtx& cx) {
;     ...
;         if (MODE == 2) {
;             const int lk0 = c_l0 - 64 + 64 * j;
; #pragma unroll
;             for (int i = 0; i < 16; ++i) {
;                 const int lka = lk0 + crow(i, h), lkb = lka + 32;
;                 const bool v0 = (lka >= 0) && (lka < c_L) && (abs(lka - c_lq) <= 64), v1 = (lkb >= 0) && (lkb < c_L) && (abs(lkb - c_lq) <= 64);
;                 s0[i] = v0 ? s0[i] : NEGBIG; s1[i] = v1 ? s1[i] : NEGBIG;
;             }
;         }
	v_cndmask_b32_e32 v20, v220, v20, vcc
	v_cmp_gt_i32_e32 vcc, s68, v51
	v_max_i32_e32 v53, v53, v54
	v_cndmask_b32_e64 v4, v220, v4, s[0:1]
	v_or_b32_e32 v52, 35, v50
	v_cmp_gt_u32_e64 s[0:1], s20, v53
	s_and_b64 s[38:39], s[54:55], vcc
	s_and_b64 vcc, s[38:39], s[0:1]
	v_cmp_lt_i32_e64 s[0:1], s21, v51
	v_sub_u32_e32 v51, v52, v0
	v_cmp_gt_i32_e64 s[38:39], s68, v52
	v_sub_u32_e32 v52, 0, v51
	v_max_i32_e32 v51, v51, v52
	v_cmp_gt_u32_e64 s[40:41], s20, v51
	v_or_b32_e32 v51, 8, v50
	v_sub_u32_e32 v53, v51, v0
	s_and_b64 s[0:1], s[0:1], s[38:39]
	v_sub_u32_e32 v54, 0, v53
	s_and_b64 s[0:1], s[0:1], s[40:41]
	v_cndmask_b32_e32 v21, v220, v21, vcc
	v_cmp_gt_i32_e32 vcc, s68, v51
	v_max_i32_e32 v53, v53, v54
	v_cndmask_b32_e64 v5, v220, v5, s[0:1]
	v_or_b32_e32 v52, 40, v50
	v_cmp_gt_u32_e64 s[0:1], s20, v53
	s_and_b64 s[38:39], s[54:55], vcc
	s_and_b64 vcc, s[38:39], s[0:1]
	v_cmp_lt_i32_e64 s[0:1], s21, v51
	v_sub_u32_e32 v51, v52, v0
	v_cmp_gt_i32_e64 s[38:39], s68, v52
	v_sub_u32_e32 v52, 0, v51
	v_max_i32_e32 v51, v51, v52
	v_cmp_gt_u32_e64 s[40:41], s20, v51
	v_or_b32_e32 v51, 9, v50
	v_sub_u32_e32 v53, v51, v0
	s_and_b64 s[0:1], s[0:1], s[38:39]
	v_sub_u32_e32 v54, 0, v53
	s_and_b64 s[0:1], s[0:1], s[40:41]
	v_cndmask_b32_e32 v22, v220, v22, vcc
	v_cmp_gt_i32_e32 vcc, s68, v51
	v_max_i32_e32 v53, v53, v54
	v_cndmask_b32_e64 v6, v220, v6, s[0:1]
	v_or_b32_e32 v52, 41, v50
	v_cmp_gt_u32_e64 s[0:1], s20, v53
	s_and_b64 s[38:39], s[54:55], vcc
	s_and_b64 vcc, s[38:39], s[0:1]
	v_cmp_lt_i32_e64 s[0:1], s21, v51
	v_sub_u32_e32 v51, v52, v0
	v_cmp_gt_i32_e64 s[38:39], s68, v52
	v_sub_u32_e32 v52, 0, v51
	v_max_i32_e32 v51, v51, v52
	v_cmp_gt_u32_e64 s[40:41], s20, v51
	v_or_b32_e32 v51, 10, v50
	v_sub_u32_e32 v53, v51, v0
	s_and_b64 s[0:1], s[0:1], s[38:39]
	v_sub_u32_e32 v54, 0, v53
	s_and_b64 s[0:1], s[0:1], s[40:41]
	v_cndmask_b32_e32 v23, v220, v23, vcc
	v_cmp_gt_i32_e32 vcc, s68, v51
	v_max_i32_e32 v53, v53, v54
	v_cndmask_b32_e64 v7, v220, v7, s[0:1]
	v_or_b32_e32 v52, 42, v50
	v_cmp_gt_u32_e64 s[0:1], s20, v53
	s_and_b64 s[38:39], s[54:55], vcc
	s_and_b64 vcc, s[38:39], s[0:1]
	v_cmp_lt_i32_e64 s[0:1], s21, v51
	v_sub_u32_e32 v51, v52, v0
	v_cmp_gt_i32_e64 s[38:39], s68, v52
	v_sub_u32_e32 v52, 0, v51
	v_max_i32_e32 v51, v51, v52
	v_cmp_gt_u32_e64 s[40:41], s20, v51
	v_or_b32_e32 v51, 11, v50
	v_sub_u32_e32 v53, v51, v0
	s_and_b64 s[0:1], s[0:1], s[38:39]
	v_sub_u32_e32 v54, 0, v53
	s_and_b64 s[0:1], s[0:1], s[40:41]
	v_cndmask_b32_e32 v24, v220, v24, vcc
	v_cmp_gt_i32_e32 vcc, s68, v51
	v_max_i32_e32 v53, v53, v54
	v_cndmask_b32_e64 v8, v220, v8, s[0:1]
	v_or_b32_e32 v52, 43, v50
	v_cmp_gt_u32_e64 s[0:1], s20, v53
	s_and_b64 s[38:39], s[54:55], vcc
	s_and_b64 vcc, s[38:39], s[0:1]
	v_cmp_lt_i32_e64 s[0:1], s21, v51
	v_sub_u32_e32 v51, v52, v0
	v_cmp_gt_i32_e64 s[38:39], s68, v52
	v_sub_u32_e32 v52, 0, v51
	v_max_i32_e32 v51, v51, v52
	v_cmp_gt_u32_e64 s[40:41], s20, v51
	v_or_b32_e32 v51, 16, v50
	v_sub_u32_e32 v53, v51, v0
	s_and_b64 s[0:1], s[0:1], s[38:39]
	v_sub_u32_e32 v54, 0, v53
	s_and_b64 s[0:1], s[0:1], s[40:41]
	v_cndmask_b32_e32 v25, v220, v25, vcc
	v_cmp_gt_i32_e32 vcc, s68, v51
	v_max_i32_e32 v53, v53, v54
	v_cndmask_b32_e64 v9, v220, v9, s[0:1]
	v_or_b32_e32 v52, 48, v50
	v_cmp_gt_u32_e64 s[0:1], s20, v53
	s_and_b64 s[38:39], s[54:55], vcc
	s_and_b64 vcc, s[38:39], s[0:1]
	v_cmp_lt_i32_e64 s[0:1], s21, v51
	v_sub_u32_e32 v51, v52, v0
	v_cmp_gt_i32_e64 s[38:39], s68, v52
	v_sub_u32_e32 v52, 0, v51
	v_max_i32_e32 v51, v51, v52
	v_cmp_gt_u32_e64 s[40:41], s20, v51
	v_or_b32_e32 v51, 17, v50
	v_sub_u32_e32 v53, v51, v0
	s_and_b64 s[0:1], s[0:1], s[38:39]
	v_sub_u32_e32 v54, 0, v53
	s_and_b64 s[0:1], s[0:1], s[40:41]
	v_cndmask_b32_e32 v26, v220, v26, vcc
	v_cmp_gt_i32_e32 vcc, s68, v51
	v_max_i32_e32 v53, v53, v54
	v_cndmask_b32_e64 v10, v220, v10, s[0:1]
	v_or_b32_e32 v52, 49, v50
	v_cmp_gt_u32_e64 s[0:1], s20, v53
	s_and_b64 s[38:39], s[54:55], vcc
	s_and_b64 vcc, s[38:39], s[0:1]
	v_cmp_lt_i32_e64 s[0:1], s21, v51
	v_sub_u32_e32 v51, v52, v0
	v_cmp_gt_i32_e64 s[38:39], s68, v52
	v_sub_u32_e32 v52, 0, v51
	v_max_i32_e32 v51, v51, v52
	v_cmp_gt_u32_e64 s[40:41], s20, v51
	v_or_b32_e32 v51, 18, v50
	v_sub_u32_e32 v53, v51, v0
	s_and_b64 s[0:1], s[0:1], s[38:39]
	v_sub_u32_e32 v54, 0, v53
	s_and_b64 s[0:1], s[0:1], s[40:41]
	v_cndmask_b32_e32 v27, v220, v27, vcc
	v_cmp_gt_i32_e32 vcc, s68, v51
	v_max_i32_e32 v53, v53, v54
	v_cndmask_b32_e64 v11, v220, v11, s[0:1]
	v_or_b32_e32 v52, 50, v50
	v_cmp_gt_u32_e64 s[0:1], s20, v53
	s_and_b64 s[38:39], s[54:55], vcc
	s_and_b64 vcc, s[38:39], s[0:1]
	v_cmp_lt_i32_e64 s[0:1], s21, v51
	v_sub_u32_e32 v51, v52, v0
	v_cmp_gt_i32_e64 s[38:39], s68, v52
	v_sub_u32_e32 v52, 0, v51
	v_max_i32_e32 v51, v51, v52
	v_cmp_gt_u32_e64 s[40:41], s20, v51
	v_or_b32_e32 v51, 19, v50
	v_sub_u32_e32 v53, v51, v0
	s_and_b64 s[0:1], s[0:1], s[38:39]
	v_sub_u32_e32 v54, 0, v53
	s_and_b64 s[0:1], s[0:1], s[40:41]
	v_cndmask_b32_e32 v28, v220, v28, vcc
	v_cmp_gt_i32_e32 vcc, s68, v51
	v_max_i32_e32 v53, v53, v54
	v_cndmask_b32_e64 v12, v220, v12, s[0:1]
	v_or_b32_e32 v52, 51, v50
	v_cmp_gt_u32_e64 s[0:1], s20, v53
	s_and_b64 s[38:39], s[54:55], vcc
	s_and_b64 vcc, s[38:39], s[0:1]
	v_cmp_lt_i32_e64 s[0:1], s21, v51
	v_sub_u32_e32 v51, v52, v0
	v_cmp_gt_i32_e64 s[38:39], s68, v52
	v_sub_u32_e32 v52, 0, v51
	v_max_i32_e32 v51, v51, v52
	v_cmp_gt_u32_e64 s[40:41], s20, v51
	v_or_b32_e32 v51, 24, v50
	v_sub_u32_e32 v53, v51, v0
	s_and_b64 s[0:1], s[0:1], s[38:39]
	v_sub_u32_e32 v54, 0, v53
	s_and_b64 s[0:1], s[0:1], s[40:41]
	v_cndmask_b32_e32 v29, v220, v29, vcc
	v_cmp_gt_i32_e32 vcc, s68, v51
; __device__ __forceinline__ int crow(int i, int h) { return (i & 3) + 8 * (i >> 2) + 4 * h; }
; __device__ __forceinline__ float max3f(float a, float b, float c) { float r; asm("v_max3_f32 %0, %1, %2, %3" : "=v"(r) : "v"(a), "v"(b), "v"(c)); return r; }
; template <int DQK, int DV, int MODE>
; __device__ __forceinline__ void attn_item(LAS unsigned char* lds, int item, const AttnCtx& cx) {
;     ...
;         if (MODE == 2) {
;             const int lk0 = c_l0 - 64 + 64 * j;
; #pragma unroll
;             for (int i = 0; i < 16; ++i) {
;                 const int lka = lk0 + crow(i, h), lkb = lka + 32;
;                 const bool v0 = (lka >= 0) && (lka < c_L) && (abs(lka - c_lq) <= 64), v1 = (lkb >= 0) && (lkb < c_L) && (abs(lkb - c_lq) <= 64);
;                 s0[i] = v0 ? s0[i] : NEGBIG; s1[i] = v1 ? s1[i] : NEGBIG;
;             }
;         }
;         float mx = max3f(s0[0], s1[0], s0[1]);
;         mx = max3f(mx, s1[1], s0[2]);
; #pragma unroll
;         for (int i = 2; i < 15; ++i) mx = max3f(mx, s1[i], s0[i + 1]);
;         mx = fmaxf(mx, s1[15]);
;         { auto rr = __builtin_amdgcn_permlane32_swap(__float_as_uint(mx), __float_as_uint(mx), false, false); mx = max3f(__uint_as_float(rr[0]), __uint_as_float(rr[1]), __uint_as_float(rr[0])); }
	v_max_i32_e32 v53, v53, v54
	v_cndmask_b32_e64 v13, v220, v13, s[0:1]
	v_or_b32_e32 v52, 56, v50
	v_cmp_gt_u32_e64 s[0:1], s20, v53
	s_and_b64 s[38:39], s[54:55], vcc
	s_and_b64 vcc, s[38:39], s[0:1]
	v_cmp_lt_i32_e64 s[0:1], s21, v51
	v_sub_u32_e32 v51, v52, v0
	v_cmp_gt_i32_e64 s[38:39], s68, v52
	v_sub_u32_e32 v52, 0, v51
	v_max_i32_e32 v51, v51, v52
	v_cmp_gt_u32_e64 s[40:41], s20, v51
	v_or_b32_e32 v51, 25, v50
	v_sub_u32_e32 v53, v51, v0
	s_and_b64 s[0:1], s[0:1], s[38:39]
	v_sub_u32_e32 v54, 0, v53
	s_and_b64 s[0:1], s[0:1], s[40:41]
	v_cndmask_b32_e32 v30, v220, v30, vcc
	v_cmp_gt_i32_e32 vcc, s68, v51
	v_max_i32_e32 v53, v53, v54
	v_cndmask_b32_e64 v14, v220, v14, s[0:1]
	v_or_b32_e32 v52, 57, v50
	v_cmp_gt_u32_e64 s[0:1], s20, v53
	s_and_b64 s[38:39], s[54:55], vcc
	s_and_b64 vcc, s[38:39], s[0:1]
	v_cmp_lt_i32_e64 s[0:1], s21, v51
	v_sub_u32_e32 v51, v52, v0
	v_cmp_gt_i32_e64 s[38:39], s68, v52
	v_sub_u32_e32 v52, 0, v51
	v_max_i32_e32 v51, v51, v52
	v_cmp_gt_u32_e64 s[40:41], s20, v51
	v_or_b32_e32 v51, 26, v50
	v_sub_u32_e32 v53, v51, v0
	s_and_b64 s[0:1], s[0:1], s[38:39]
	v_sub_u32_e32 v54, 0, v53
	s_and_b64 s[0:1], s[0:1], s[40:41]
	v_cndmask_b32_e32 v31, v220, v31, vcc
	v_cmp_gt_i32_e32 vcc, s68, v51
	v_max_i32_e32 v53, v53, v54
	v_cndmask_b32_e64 v15, v220, v15, s[0:1]
	v_or_b32_e32 v52, 58, v50
	v_cmp_gt_u32_e64 s[0:1], s20, v53
	s_and_b64 s[38:39], s[54:55], vcc
	s_and_b64 vcc, s[38:39], s[0:1]
	v_cmp_lt_i32_e64 s[0:1], s21, v51
	v_sub_u32_e32 v51, v52, v0
	v_cmp_gt_i32_e64 s[38:39], s68, v52
	v_sub_u32_e32 v52, 0, v51
	v_max_i32_e32 v51, v51, v52
	v_cmp_gt_u32_e64 s[40:41], s20, v51
	v_or_b32_e32 v51, 27, v50
	v_sub_u32_e32 v52, v51, v0
	s_and_b64 s[0:1], s[0:1], s[38:39]
	v_sub_u32_e32 v53, 0, v52
	s_and_b64 s[0:1], s[0:1], s[40:41]
	v_cndmask_b32_e32 v32, v220, v32, vcc
	v_or_b32_e32 v50, 59, v50
	v_cmp_gt_i32_e32 vcc, s68, v51
	v_max_i32_e32 v52, v52, v53
	v_cndmask_b32_e64 v16, v220, v16, s[0:1]
	v_cmp_gt_u32_e64 s[0:1], s20, v52
	s_and_b64 s[38:39], s[54:55], vcc
	v_sub_u32_e32 v0, v50, v0
	s_and_b64 vcc, s[38:39], s[0:1]
	v_cmp_gt_i32_e64 s[38:39], s68, v50
	v_sub_u32_e32 v50, 0, v0
	v_max_i32_e32 v0, v0, v50
	v_cmp_gt_u32_e64 s[40:41], s20, v0
	v_cndmask_b32_e32 v0, v220, v33, vcc
	v_max3_f32 v33, v18, v2, v19
	v_cmp_lt_i32_e64 s[0:1], s21, v51
	v_max3_f32 v33, v33, v3, v20
	s_and_b64 s[0:1], s[0:1], s[38:39]
	v_max3_f32 v33, v33, v4, v21
	s_and_b64 s[0:1], s[0:1], s[40:41]
	v_max3_f32 v33, v33, v5, v22
	v_cndmask_b32_e64 v17, v220, v17, s[0:1]
	v_max3_f32 v33, v33, v6, v23
	v_max_f32_e32 v50, v17, v17
	v_max3_f32 v33, v33, v7, v24
	s_mov_b32 s89, s88
	v_max3_f32 v33, v33, v8, v25
	s_mov_b32 s90, s88
	v_max3_f32 v33, v33, v9, v26
	s_mov_b32 s91, s88
	v_max3_f32 v33, v33, v10, v27
	ds_read_b64_tr_b16 v[46:47], v119 offset:0
	ds_read_b64_tr_b16 v[48:49], v119 offset:2560
	ds_read_b64_tr_b16 v[42:43], v119 offset:5120
	ds_read_b64_tr_b16 v[44:45], v119 offset:7680
	ds_read_b64_tr_b16 v[38:39], v119 offset:10240
	s_nop 0
	v_max3_f32 v33, v33, v11, v28
	ds_read_b64_tr_b16 v[40:41], v119 offset:12800
	ds_read_b64_tr_b16 v[34:35], v119 offset:15360
	ds_read_b64_tr_b16 v[36:37], v119 offset:17920
	s_waitcnt lgkmcnt(0)
; #define LGKM0() asm volatile("s_waitcnt lgkmcnt(0)" ::: "memory")
; template <int DQK, int DV, int MODE>
; __device__ __forceinline__ void attn_item(LAS unsigned char* lds, int item, const AttnCtx& cx) {
;     ...
;         float mx = max3f(s0[0], s1[0], s0[1]);
;         mx = max3f(mx, s1[1], s0[2]);
; #pragma unroll
;         for (int i = 2; i < 15; ++i) mx = max3f(mx, s1[i], s0[i + 1]);
;         mx = fmaxf(mx, s1[15]);
;         { auto rr = __builtin_amdgcn_permlane32_swap(__float_as_uint(mx), __float_as_uint(mx), false, false); mx = max3f(__uint_as_float(rr[0]), __uint_as_float(rr[1]), __uint_as_float(rr[0])); }
;         if (first || __builtin_amdgcn_ballot_w64(mx > THR) != 0ull) {
;             const float delta = first ? mx : fmaxf(mx, 0.f), alpha = fast_exp2(-delta);
; #pragma unroll
;             for (int i = 0; i < 16; ++i) { s0[i] -= delta; s1[i] -= delta; }
;             if (!first) {
; #pragma unroll
;                 for (int d = 0; d < NDV; ++d)
; #pragma unroll
;                     for (int i = 0; i < 16; ++i) O[d][i] *= alpha;
; #pragma unroll
;                 for (int i = 0; i < 16; ++i) Lacc[i] *= alpha;
;             }
;             mhat += delta;
; #pragma unroll
;             for (int i = 0; i < 16; ++i) negm[i] = -mhat;
;             if (MODE == 1) set_cin();
;             first = false;
;         }
; #pragma unroll
;         for (int i = 0; i < 16; ++i) { s0[i] = fast_exp2(s0[i]); s1[i] = fast_exp2(s1[i]); }
;         u32x4 w;
;         w.x = pk2(s0[0], s0[1]); w.y = pk2(s0[2], s0[3]); w.z = pk2(s0[4], s0[5]); w.w = pk2(s0[6], s0[7]); pa[0][0] = __builtin_bit_cast(bf16x8, w);
;         w.x = pk2(s0[8], s0[9]); w.y = pk2(s0[10], s0[11]); w.z = pk2(s0[12], s0[13]); w.w = pk2(s0[14], s0[15]); pa[0][1] = __builtin_bit_cast(bf16x8, w);
;         w.x = pk2(s1[0], s1[1]); w.y = pk2(s1[2], s1[3]); w.z = pk2(s1[4], s1[5]); w.w = pk2(s1[6], s1[7]); pa[1][0] = __builtin_bit_cast(bf16x8, w);
;         w.x = pk2(s1[8], s1[9]); w.y = pk2(s1[10], s1[11]); w.z = pk2(s1[12], s1[13]); w.w = pk2(s1[14], s1[15]); pa[1][1] = __builtin_bit_cast(bf16x8, w);
;     };
;     auto do_pv = [&](unsigned va) {
; #pragma unroll
;         for (int k4 = 0; k4 < 4; ++k4) Lacc = MFMA32(ones8, pa[k4 >> 1][k4 & 1], Lacc);
; #pragma unroll
;         for (int d = 0; d < NDV; ++d) {
;             LGKM0(); SBAR();
; #pragma unroll
;             for (int k4 = 0; k4 < 4; ++k4) {
	s_nop 0
	v_max3_f32 v33, v33, v12, v29
	s_nop 0
	v_max3_f32 v33, v33, v13, v30
	s_nop 0
	v_max3_f32 v33, v33, v14, v31
	s_nop 0
	v_max3_f32 v33, v33, v15, v32
	s_nop 0
	v_max3_f32 v33, v33, v16, v0
	s_nop 0
	v_max_f32_e32 v33, v33, v33
	v_max_f32_e32 v33, v33, v50
	v_mov_b32_e32 v50, v33
	s_nop 1
	v_permlane32_swap_b32_e32 v33, v50
	v_max3_f32 v33, v33, v50, v33
	v_mov_b64_e32 v[50:51], s[88:89]
	v_sub_f32_e32 v18, v18, v33
	v_sub_f32_e32 v19, v19, v33
	v_sub_f32_e32 v20, v20, v33
	v_sub_f32_e32 v21, v21, v33
	v_sub_f32_e32 v22, v22, v33
	v_sub_f32_e32 v6, v6, v33
	v_sub_f32_e32 v23, v23, v33
	v_sub_f32_e32 v7, v7, v33
	v_sub_f32_e32 v24, v24, v33
	v_sub_f32_e32 v8, v8, v33
	v_sub_f32_e32 v25, v25, v33
	v_sub_f32_e32 v2, v2, v33
	v_sub_f32_e32 v3, v3, v33
	v_sub_f32_e32 v4, v4, v33
	v_sub_f32_e32 v5, v5, v33
	v_sub_f32_e32 v9, v9, v33
	v_sub_f32_e32 v26, v26, v33
	v_sub_f32_e32 v10, v10, v33
	v_sub_f32_e32 v27, v27, v33
	v_sub_f32_e32 v11, v11, v33
	v_sub_f32_e32 v28, v28, v33
	v_sub_f32_e32 v12, v12, v33
	v_sub_f32_e32 v29, v29, v33
	v_sub_f32_e32 v13, v13, v33
	v_sub_f32_e32 v30, v30, v33
	v_sub_f32_e32 v14, v14, v33
	v_sub_f32_e32 v31, v31, v33
	v_sub_f32_e32 v15, v15, v33
	v_sub_f32_e32 v32, v32, v33
	v_sub_f32_e32 v16, v16, v33
	v_sub_f32_e32 v0, v0, v33
	v_sub_f32_e32 v17, v17, v33
	v_add_f32_e32 v213, 0, v33
	v_exp_f32_e32 v18, v18
	v_exp_f32_e32 v19, v19
	v_exp_f32_e32 v20, v20
	v_exp_f32_e32 v21, v21
	v_exp_f32_e32 v22, v22
	v_exp_f32_e32 v33, v6
	v_exp_f32_e32 v6, v23
	v_exp_f32_e32 v23, v7
	v_exp_f32_e32 v7, v24
	v_exp_f32_e32 v24, v8
	v_exp_f32_e32 v8, v25
	v_mov_b64_e32 v[52:53], s[90:91]
	v_exp_f32_e32 v2, v2
	v_exp_f32_e32 v3, v3
	v_exp_f32_e32 v4, v4
	v_exp_f32_e32 v5, v5
	v_exp_f32_e32 v9, v9
	v_exp_f32_e32 v25, v26
	v_exp_f32_e32 v26, v10
	v_exp_f32_e32 v10, v27
	v_exp_f32_e32 v27, v11
	v_exp_f32_e32 v11, v28
	v_exp_f32_e32 v28, v12
	v_exp_f32_e32 v12, v29
	v_exp_f32_e32 v29, v13
	v_exp_f32_e32 v13, v30
	v_exp_f32_e32 v30, v31
	v_exp_f32_e32 v31, v32
	v_exp_f32_e32 v16, v16
	v_exp_f32_e32 v0, v0
	v_exp_f32_e32 v17, v17
	v_cvt_pk_bf16_f32 v112, v18, v19
	v_cvt_pk_bf16_f32 v113, v20, v21
	v_cvt_pk_bf16_f32 v114, v22, v6
	v_cvt_pk_bf16_f32 v115, v7, v8
	v_cvt_pk_bf16_f32 v10, v25, v10
	v_cvt_pk_bf16_f32 v11, v11, v12
	v_cvt_pk_bf16_f32 v12, v13, v30
	v_cvt_pk_bf16_f32 v13, v31, v0
	v_cvt_pk_bf16_f32 v6, v2, v3
	v_cvt_pk_bf16_f32 v7, v4, v5
	v_cvt_pk_bf16_f32 v8, v33, v23
	v_cvt_pk_bf16_f32 v9, v24, v9
	v_cvt_pk_bf16_f32 v2, v26, v27
	v_cvt_pk_bf16_f32 v3, v28, v29
	v_cvt_pk_bf16_f32 v5, v16, v17
	v_mfma_f32_32x32x16_bf16 v[16:31], v[50:53], v[112:115], 0
	v_exp_f32_e32 v14, v14
	v_exp_f32_e32 v15, v15
	v_xor_b32_e32 v96, 0x80000000, v213
	v_mov_b32_e32 v97, v96
	v_mov_b32_e32 v98, v96
	v_cvt_pk_bf16_f32 v4, v14, v15
	v_mov_b32_e32 v99, v96
	v_mfma_f32_32x32x16_bf16 v[16:31], v[50:53], v[10:13], v[16:31]
	v_mov_b32_e32 v100, v96
	v_mov_b32_e32 v101, v96
	v_mov_b32_e32 v102, v96
	v_mov_b32_e32 v103, v96
	v_mov_b32_e32 v104, v96
	v_mov_b32_e32 v105, v96
	v_mov_b32_e32 v106, v96
	v_mfma_f32_32x32x16_bf16 v[16:31], v[50:53], v[6:9], v[16:31]
	v_mov_b32_e32 v107, v96
	v_mov_b32_e32 v108, v96
	v_mov_b32_e32 v109, v96
	v_mov_b32_e32 v110, v96
	v_mov_b32_e32 v111, v96
	v_mfma_f32_32x32x16_bf16 v[16:31], v[50:53], v[2:5], v[16:31]
	v_mfma_f32_32x32x16_bf16 v[80:95], v[46:49], v[112:115], 0
	v_mfma_f32_32x32x16_bf16 v[80:95], v[42:45], v[10:13], v[80:95]
	v_mfma_f32_32x32x16_bf16 v[80:95], v[38:41], v[6:9], v[80:95]
	v_mfma_f32_32x32x16_bf16 v[80:95], v[34:37], v[2:5], v[80:95]
	ds_read_b64_tr_b16 v[32:33], v119 offset:64
	ds_read_b64_tr_b16 v[34:35], v119 offset:2624
	ds_read_b64_tr_b16 v[36:37], v119 offset:5184
	ds_read_b64_tr_b16 v[38:39], v119 offset:7744
	ds_read_b64_tr_b16 v[40:41], v119 offset:10304
	ds_read_b64_tr_b16 v[42:43], v119 offset:12864
	ds_read_b64_tr_b16 v[44:45], v119 offset:15424
	ds_read_b64_tr_b16 v[46:47], v119 offset:17984
	s_waitcnt lgkmcnt(6)
	s_nop 0
	s_nop 0
	v_mfma_f32_32x32x16_bf16 v[64:79], v[32:35], v[112:115], 0
	s_waitcnt lgkmcnt(4)
	v_mfma_f32_32x32x16_bf16 v[64:79], v[36:39], v[10:13], v[64:79]
	s_waitcnt lgkmcnt(2)
	v_mfma_f32_32x32x16_bf16 v[64:79], v[40:43], v[6:9], v[64:79]
	s_waitcnt lgkmcnt(0)
	v_mfma_f32_32x32x16_bf16 v[64:79], v[44:47], v[2:5], v[64:79]
	ds_read_b64_tr_b16 v[32:33], v119 offset:128
	ds_read_b64_tr_b16 v[34:35], v119 offset:2688
	ds_read_b64_tr_b16 v[36:37], v119 offset:5248
	ds_read_b64_tr_b16 v[38:39], v119 offset:7808
	ds_read_b64_tr_b16 v[40:41], v119 offset:10368
	ds_read_b64_tr_b16 v[42:43], v119 offset:12928
	ds_read_b64_tr_b16 v[44:45], v119 offset:15488
	ds_read_b64_tr_b16 v[46:47], v119 offset:18048
	s_waitcnt lgkmcnt(6)
	s_nop 0
	s_nop 0
	v_mfma_f32_32x32x16_bf16 v[48:63], v[32:35], v[112:115], 0
	s_waitcnt lgkmcnt(4)
	v_mfma_f32_32x32x16_bf16 v[48:63], v[36:39], v[10:13], v[48:63]
	s_waitcnt lgkmcnt(2)
	v_mfma_f32_32x32x16_bf16 v[48:63], v[40:43], v[6:9], v[48:63]
	s_waitcnt lgkmcnt(0)
	v_mfma_f32_32x32x16_bf16 v[48:63], v[44:47], v[2:5], v[48:63]
	ds_read_b64_tr_b16 v[32:33], v119 offset:192
	ds_read_b64_tr_b16 v[34:35], v119 offset:2752
	ds_read_b64_tr_b16 v[120:121], v119 offset:5312
	ds_read_b64_tr_b16 v[122:123], v119 offset:7872
	ds_read_b64_tr_b16 v[124:125], v119 offset:10432
	ds_read_b64_tr_b16 v[126:127], v119 offset:12992
	ds_read_b64_tr_b16 v[128:129], v119 offset:15552
	ds_read_b64_tr_b16 v[130:131], v119 offset:18112
	s_waitcnt lgkmcnt(6)
	s_nop 0
	s_nop 0
	v_mfma_f32_32x32x16_bf16 v[32:47], v[32:35], v[112:115], 0
	s_waitcnt lgkmcnt(4)
	v_mfma_f32_32x32x16_bf16 v[32:47], v[120:123], v[10:13], v[32:47]
	s_waitcnt lgkmcnt(2)
	v_mfma_f32_32x32x16_bf16 v[32:47], v[124:127], v[6:9], v[32:47]
	s_waitcnt lgkmcnt(0)
	v_mfma_f32_32x32x16_bf16 v[32:47], v[128:131], v[2:5], v[32:47]
	s_mov_b64 s[56:57], 0
	s_branch .LBB0_299

; #define MFMA32(a, b, c) __builtin_amdgcn_mfma_f32_32x32x16_bf16((a), (b), (c), 0, 0, 0)
; #define LGKM0() asm volatile("s_waitcnt lgkmcnt(0)" ::: "memory")
; #define SBAR() __builtin_amdgcn_sched_barrier(0)
; #define V_ISSUE(va, b, d) do { _Pragma("unroll") for (int k4 = 0; k4 < 4; ++k4) { DS_TR16(vlo[b][k4], va, (16 * k4) * VP + (d) * 64); DS_TR16(vhi[b][k4], va, (16 * k4 + 8) * VP + (d) * 64); } } while (0)
; #define K_ISSUE(b, kb) do { DS_RD128(kfr[b][0], kaddr, (2 * (kb)) * 32); DS_RD128(kfr[b][1], kaddr, 32 * KP + (2 * (kb)) * 32); \
;                             DS_RD128(kfr[b][2], kaddr, (2 * (kb) + 1) * 32); DS_RD128(kfr[b][3], kaddr, 32 * KP + (2 * (kb) + 1) * 32); } while (0)
; template <int DQK, int DV, int MODE>
; __device__ __forceinline__ void attn_item(LAS unsigned char* lds, int item, const AttnCtx& cx) {
;     ...
;     auto do_qk = [&](int j, bool vpre) {
;         const unsigned kaddr = (unsigned)(size_t)(lds + (j % NST) * SB + koff) + r * KP + 16 * h;
;         const unsigned va = vaddr_of(j);
;         bf16x8 kfr[1][4];
;         K_ISSUE(0, 0);
; #pragma unroll
;         for (int kb = 0; kb < NQF / 2; ++kb) {
;             LGKM0(); SBAR();
;             if (kb == 0) { if (MODE == 1) { s0 = MFMA32(kfr[0][0], qf[0], cin0); s1 = MFMA32(kfr[0][1], qf[0], cin1); } else { s0 = MFMA32(kfr[0][0], qf[0], negm); s1 = MFMA32(kfr[0][1], qf[0], negm); } }
;             else { s0 = MFMA32(kfr[0][0], qf[2 * kb], s0); s1 = MFMA32(kfr[0][1], qf[2 * kb], s1); }
;             s0 = MFMA32(kfr[0][2], qf[2 * kb + 1], s0); s1 = MFMA32(kfr[0][3], qf[2 * kb + 1], s1);
;             SBAR();
;             if (kb + 1 < NQF / 2) K_ISSUE(0, kb + 1); else if (vpre) V_ISSUE(va, 0, 0);
;         }
.LBB0_309:
	s_xor_b64 s[58:59], s[56:57], -1
	s_add_i32 s0, s30, -1
	s_add_i32 s1, s30, -3
	s_cmp_lt_u32 s0, 2
	s_cselect_b32 s0, s0, s1
	s_mul_i32 s0, s0, 0x12800
	s_add_i32 s0, s70, s0
	v_add_u32_e32 v216, s0, v238
	ds_read_b128 v[2:5], v216 offset:0
	ds_read_b128 v[6:9], v216 offset:8704
	ds_read_b128 v[10:13], v216 offset:32
	ds_read_b128 v[208:211], v216 offset:8736
	s_waitcnt lgkmcnt(0)
	s_addk_i32 s0, 0x4400
	v_add_u32_e32 v241, s0, v239
	v_mfma_f32_32x32x16_bf16 v[128:143], v[2:5], v[144:147], v[96:111]
	v_mfma_f32_32x32x16_bf16 v[112:127], v[6:9], v[144:147], v[96:111]
	v_mfma_f32_32x32x16_bf16 v[128:143], v[10:13], v[148:151], v[128:143]
	v_mfma_f32_32x32x16_bf16 v[112:127], v[208:211], v[148:151], v[112:127]
	ds_read_b128 v[2:5], v216 offset:64
	ds_read_b128 v[6:9], v216 offset:8768
	ds_read_b128 v[10:13], v216 offset:96
	ds_read_b128 v[208:211], v216 offset:8800
	s_waitcnt lgkmcnt(3)
	s_nop 0
	s_nop 0
	v_mfma_f32_32x32x16_bf16 v[128:143], v[2:5], v[152:155], v[128:143]
	s_waitcnt lgkmcnt(2)
	v_mfma_f32_32x32x16_bf16 v[112:127], v[6:9], v[152:155], v[112:127]
	s_waitcnt lgkmcnt(1)
	v_mfma_f32_32x32x16_bf16 v[128:143], v[10:13], v[156:159], v[128:143]
	s_waitcnt lgkmcnt(0)
	v_mfma_f32_32x32x16_bf16 v[112:127], v[208:211], v[156:159], v[112:127]
	ds_read_b128 v[2:5], v216 offset:128
	ds_read_b128 v[6:9], v216 offset:8832
	ds_read_b128 v[10:13], v216 offset:160
	ds_read_b128 v[208:211], v216 offset:8864
	s_waitcnt lgkmcnt(3)
	s_nop 0
	s_nop 0
	v_mfma_f32_32x32x16_bf16 v[128:143], v[2:5], v[160:163], v[128:143]
	s_waitcnt lgkmcnt(2)
	v_mfma_f32_32x32x16_bf16 v[112:127], v[6:9], v[160:163], v[112:127]
	s_waitcnt lgkmcnt(1)
	v_mfma_f32_32x32x16_bf16 v[128:143], v[10:13], v[164:167], v[128:143]
	s_waitcnt lgkmcnt(0)
	v_mfma_f32_32x32x16_bf16 v[112:127], v[208:211], v[164:167], v[112:127]
	ds_read_b128 v[2:5], v216 offset:192
	ds_read_b128 v[6:9], v216 offset:8896
	ds_read_b128 v[10:13], v216 offset:224
	ds_read_b128 v[208:211], v216 offset:8928
	s_waitcnt lgkmcnt(3)
	s_nop 0
	s_nop 0
	v_mfma_f32_32x32x16_bf16 v[128:143], v[2:5], v[168:171], v[128:143]
	s_waitcnt lgkmcnt(2)
	v_mfma_f32_32x32x16_bf16 v[112:127], v[6:9], v[168:171], v[112:127]
	s_waitcnt lgkmcnt(1)
	v_mfma_f32_32x32x16_bf16 v[128:143], v[10:13], v[172:175], v[128:143]
	s_waitcnt lgkmcnt(0)
; __device__ __forceinline__ int crow(int i, int h) { return (i & 3) + 8 * (i >> 2) + 4 * h; }
; __device__ __forceinline__ float max3f(float a, float b, float c) { float r; asm("v_max3_f32 %0, %1, %2, %3" : "=v"(r) : "v"(a), "v"(b), "v"(c)); return r; }
; template <int DQK, int DV, int MODE>
; __device__ __forceinline__ void attn_item(LAS unsigned char* lds, int item, const AttnCtx& cx) {
;     ...
;         if (MODE == 2) {
;             const int lk0 = c_l0 - 64 + 64 * j;
; #pragma unroll
;             for (int i = 0; i < 16; ++i) {
;                 const int lka = lk0 + crow(i, h), lkb = lka + 32;
;                 const bool v0 = (lka >= 0) && (lka < c_L) && (abs(lka - c_lq) <= 64), v1 = (lkb >= 0) && (lkb < c_L) && (abs(lkb - c_lq) <= 64);
;                 s0[i] = v0 ? s0[i] : NEGBIG; s1[i] = v1 ? s1[i] : NEGBIG;
;             }
;         }
;         float mx = max3f(s0[0], s1[0], s0[1]);
;         mx = max3f(mx, s1[1], s0[2]);
; #pragma unroll
;         for (int i = 2; i < 15; ++i) mx = max3f(mx, s1[i], s0[i + 1]);
;         mx = fmaxf(mx, s1[15]);
;         { auto rr = __builtin_amdgcn_permlane32_swap(__float_as_uint(mx), __float_as_uint(mx), false, false); mx = max3f(__uint_as_float(rr[0]), __uint_as_float(rr[1]), __uint_as_float(rr[0])); }
;         if (first || __builtin_amdgcn_ballot_w64(mx > THR) != 0ull) {
	v_mfma_f32_32x32x16_bf16 v[112:127], v[208:211], v[172:175], v[112:127]
	v_add_u32_e32 v222, s71, v15
	v_add_u32_e32 v216, s71, v240
	v_sub_u32_e32 v223, 0, v216
	v_sub_u32_e32 v224, 0xffffffc0, v222
	v_max_i32_e32 v223, v223, v224
	s_add_i32 s0, s68, -1
	v_sub_u32_e32 v224, s0, v216
	v_sub_u32_e32 v225, 64, v222
	v_min_i32_e32 v224, v224, v225
	v_sub_u32_e32 v224, v224, v223
	v_cmp_gt_i32_e32 vcc, 0, v224
	v_mov_b32_e32 v225, 0x40000000
	v_cndmask_b32_e32 v223, v223, v225, vcc
	v_max_i32_e32 v224, 0, v224
	v_sub_u32_e32 v216, 0, v223
	v_sub_u32_e32 v217, 32, v223
	v_sub_u32_e32 v222, 1, v223
	v_sub_u32_e32 v225, 33, v223
	v_cmp_ge_u32_e32 vcc, v224, v216
	v_cmp_ge_u32_e64 s[0:1], v224, v217
	v_cmp_ge_u32_e64 s[38:39], v224, v222
	v_cmp_ge_u32_e64 s[40:41], v224, v225
	v_cndmask_b32_e32 v128, v220, v128, vcc
	v_cndmask_b32_e64 v112, v220, v112, s[0:1]
	v_cndmask_b32_e64 v129, v220, v129, s[38:39]
	v_cndmask_b32_e64 v113, v220, v113, s[40:41]
	v_sub_u32_e32 v216, 2, v223
	v_sub_u32_e32 v217, 34, v223
	v_sub_u32_e32 v222, 3, v223
	v_sub_u32_e32 v225, 35, v223
	v_cmp_ge_u32_e32 vcc, v224, v216
	v_cmp_ge_u32_e64 s[0:1], v224, v217
	v_cmp_ge_u32_e64 s[38:39], v224, v222
	v_cmp_ge_u32_e64 s[40:41], v224, v225
	v_cndmask_b32_e32 v130, v220, v130, vcc
	v_cndmask_b32_e64 v114, v220, v114, s[0:1]
	v_cndmask_b32_e64 v131, v220, v131, s[38:39]
	v_cndmask_b32_e64 v115, v220, v115, s[40:41]
	v_sub_u32_e32 v216, 8, v223
	v_sub_u32_e32 v217, 40, v223
	v_sub_u32_e32 v222, 9, v223
	v_sub_u32_e32 v225, 41, v223
	v_cmp_ge_u32_e32 vcc, v224, v216
	v_cmp_ge_u32_e64 s[0:1], v224, v217
	v_cmp_ge_u32_e64 s[38:39], v224, v222
	v_cmp_ge_u32_e64 s[40:41], v224, v225
	v_cndmask_b32_e32 v132, v220, v132, vcc
	v_cndmask_b32_e64 v116, v220, v116, s[0:1]
	v_cndmask_b32_e64 v133, v220, v133, s[38:39]
	v_cndmask_b32_e64 v117, v220, v117, s[40:41]
	v_sub_u32_e32 v216, 10, v223
	v_sub_u32_e32 v217, 42, v223
	v_sub_u32_e32 v222, 11, v223
	v_sub_u32_e32 v225, 43, v223
	v_cmp_ge_u32_e32 vcc, v224, v216
	v_cmp_ge_u32_e64 s[0:1], v224, v217
	v_cmp_ge_u32_e64 s[38:39], v224, v222
	v_cmp_ge_u32_e64 s[40:41], v224, v225
	v_cndmask_b32_e32 v134, v220, v134, vcc
	v_cndmask_b32_e64 v118, v220, v118, s[0:1]
	v_cndmask_b32_e64 v135, v220, v135, s[38:39]
	v_cndmask_b32_e64 v119, v220, v119, s[40:41]
	v_sub_u32_e32 v216, 16, v223
	v_sub_u32_e32 v217, 48, v223
	v_sub_u32_e32 v222, 17, v223
	v_sub_u32_e32 v225, 49, v223
	v_cmp_ge_u32_e32 vcc, v224, v216
	v_cmp_ge_u32_e64 s[0:1], v224, v217
	v_cmp_ge_u32_e64 s[38:39], v224, v222
	v_cmp_ge_u32_e64 s[40:41], v224, v225
	v_cndmask_b32_e32 v136, v220, v136, vcc
	v_cndmask_b32_e64 v120, v220, v120, s[0:1]
	v_cndmask_b32_e64 v137, v220, v137, s[38:39]
	v_cndmask_b32_e64 v121, v220, v121, s[40:41]
	v_sub_u32_e32 v216, 18, v223
	v_sub_u32_e32 v217, 50, v223
	v_sub_u32_e32 v222, 19, v223
	v_sub_u32_e32 v225, 51, v223
	v_cmp_ge_u32_e32 vcc, v224, v216
	v_cmp_ge_u32_e64 s[0:1], v224, v217
	v_cmp_ge_u32_e64 s[38:39], v224, v222
	v_cmp_ge_u32_e64 s[40:41], v224, v225
	v_cndmask_b32_e32 v138, v220, v138, vcc
	v_cndmask_b32_e64 v122, v220, v122, s[0:1]
	v_cndmask_b32_e64 v139, v220, v139, s[38:39]
	v_cndmask_b32_e64 v123, v220, v123, s[40:41]
	v_sub_u32_e32 v216, 24, v223
	v_sub_u32_e32 v217, 56, v223
	v_sub_u32_e32 v222, 25, v223
	v_sub_u32_e32 v225, 57, v223
	v_cmp_ge_u32_e32 vcc, v224, v216
	v_cmp_ge_u32_e64 s[0:1], v224, v217
	v_cmp_ge_u32_e64 s[38:39], v224, v222
	v_cmp_ge_u32_e64 s[40:41], v224, v225
	v_cndmask_b32_e32 v140, v220, v140, vcc
	v_cndmask_b32_e64 v124, v220, v124, s[0:1]
	v_cndmask_b32_e64 v141, v220, v141, s[38:39]
	v_cndmask_b32_e64 v125, v220, v125, s[40:41]
	v_sub_u32_e32 v216, 26, v223
	v_sub_u32_e32 v217, 58, v223
	v_sub_u32_e32 v222, 27, v223
	v_sub_u32_e32 v225, 59, v223
	v_cmp_ge_u32_e32 vcc, v224, v216
	v_cmp_ge_u32_e64 s[0:1], v224, v217
	v_cmp_ge_u32_e64 s[38:39], v224, v222
	v_cmp_ge_u32_e64 s[40:41], v224, v225
	v_cndmask_b32_e32 v142, v220, v142, vcc
	v_cndmask_b32_e64 v126, v220, v126, s[0:1]
	v_cndmask_b32_e64 v143, v220, v143, s[38:39]
	v_cndmask_b32_e64 v127, v220, v127, s[40:41]
	v_max3_f32 v216, v128, v112, v129
	ds_read_b64_tr_b16 v[208:209], v241 offset:0
	ds_read_b64_tr_b16 v[210:211], v241 offset:2560
	v_max3_f32 v216, v216, v113, v130
	ds_read_b64_tr_b16 v[10:11], v241 offset:5120
	v_max3_f32 v216, v216, v114, v131
	ds_read_b64_tr_b16 v[12:13], v241 offset:7680
	v_max3_f32 v216, v216, v115, v132
	v_max3_f32 v216, v216, v116, v133
	ds_read_b64_tr_b16 v[6:7], v241 offset:10240
	v_max_f32_e32 v217, v127, v127
	v_max3_f32 v216, v216, v117, v134
	ds_read_b64_tr_b16 v[8:9], v241 offset:12800
	ds_read_b64_tr_b16 v[2:3], v241 offset:15360
	ds_read_b64_tr_b16 v[4:5], v241 offset:17920
	s_andn2_b64 vcc, exec, s[58:59]
	v_max3_f32 v216, v216, v118, v135
	s_mov_b64 s[38:39], s[56:57]
	v_max3_f32 v216, v216, v119, v136
	s_nop 0
	v_max3_f32 v216, v216, v120, v137
	s_nop 0
	v_max3_f32 v216, v216, v121, v138
	s_nop 0
	v_max3_f32 v216, v216, v122, v139
	s_nop 0
	v_max3_f32 v216, v216, v123, v140
	s_nop 0
	v_max3_f32 v216, v216, v124, v141
	s_nop 0
	v_max3_f32 v216, v216, v125, v142
	s_nop 0
	v_max3_f32 v216, v216, v126, v143
	s_nop 0
	v_max_f32_e32 v216, v216, v216
	v_max_f32_e32 v216, v216, v217
	v_mov_b32_e32 v217, v216
	s_nop 1
	v_permlane32_swap_b32_e32 v216, v217
	v_max3_f32 v242, v216, v217, v216
	v_cndmask_b32_e64 v216, 0, 1, s[58:59]
	v_cmp_ne_u32_e64 s[0:1], 1, v216
	s_cbranch_vccnz .LBB0_311
	v_cmp_lt_f32_e32 vcc, s29, v242
	s_cmp_lg_u64 vcc, 0
	s_cselect_b64 s[38:39], -1, 0

; __device__ __forceinline__ unsigned pk2(float lo, float hi) { f32x2 v = {lo, hi}; bf16x2_t b = __builtin_convertvector(v, bf16x2_t); return __builtin_bit_cast(unsigned, b); }
; __device__ __forceinline__ float fast_exp2(float x) { return __builtin_amdgcn_exp2f(x); }
; #define MFMA32(a, b, c) __builtin_amdgcn_mfma_f32_32x32x16_bf16((a), (b), (c), 0, 0, 0)
; #define LGKM0() asm volatile("s_waitcnt lgkmcnt(0)" ::: "memory")
; #define SBAR() __builtin_amdgcn_sched_barrier(0)
; #define V_ISSUE(va, b, d) do { _Pragma("unroll") for (int k4 = 0; k4 < 4; ++k4) { DS_TR16(vlo[b][k4], va, (16 * k4) * VP + (d) * 64); DS_TR16(vhi[b][k4], va, (16 * k4 + 8) * VP + (d) * 64); } } while (0)
; template <int DQK, int DV, int MODE>
; __device__ __forceinline__ void attn_item(LAS unsigned char* lds, int item, const AttnCtx& cx) {
;     ...
; #pragma unroll
;         for (int i = 0; i < 16; ++i) { s0[i] = fast_exp2(s0[i]); s1[i] = fast_exp2(s1[i]); }
;         u32x4 w;
;         w.x = pk2(s0[0], s0[1]); w.y = pk2(s0[2], s0[3]); w.z = pk2(s0[4], s0[5]); w.w = pk2(s0[6], s0[7]); pa[0][0] = __builtin_bit_cast(bf16x8, w);
;         w.x = pk2(s0[8], s0[9]); w.y = pk2(s0[10], s0[11]); w.z = pk2(s0[12], s0[13]); w.w = pk2(s0[14], s0[15]); pa[0][1] = __builtin_bit_cast(bf16x8, w);
;         w.x = pk2(s1[0], s1[1]); w.y = pk2(s1[2], s1[3]); w.z = pk2(s1[4], s1[5]); w.w = pk2(s1[6], s1[7]); pa[1][0] = __builtin_bit_cast(bf16x8, w);
;         w.x = pk2(s1[8], s1[9]); w.y = pk2(s1[10], s1[11]); w.z = pk2(s1[12], s1[13]); w.w = pk2(s1[14], s1[15]); pa[1][1] = __builtin_bit_cast(bf16x8, w);
;     };
;     auto do_pv = [&](unsigned va) {
; #pragma unroll
;         for (int k4 = 0; k4 < 4; ++k4) Lacc = MFMA32(ones8, pa[k4 >> 1][k4 & 1], Lacc);
; #pragma unroll
;         for (int d = 0; d < NDV; ++d) {
;             LGKM0(); SBAR();
; #pragma unroll
;             for (int k4 = 0; k4 < 4; ++k4) {
;                 const bf16x8 vf = __builtin_shufflevector(vlo[d & 1][k4], vhi[d & 1][k4], 0, 1, 2, 3, 4, 5, 6, 7);
;                 O[d] = MFMA32(vf, pa[k4 >> 1][k4 & 1], O[d]);
;             }
;             SBAR();
;             if (d + 1 < NDV) V_ISSUE(va, (d + 1) & 1, d + 1);
.LBB0_315:
	v_exp_f32_e32 v128, v128
	v_exp_f32_e32 v129, v129
	v_exp_f32_e32 v130, v130
	v_exp_f32_e32 v131, v131
	s_mov_b32 s90, s88
	s_mov_b32 s91, s88
	v_exp_f32_e32 v216, v116
	v_exp_f32_e32 v116, v133
	v_exp_f32_e32 v133, v117
	v_exp_f32_e32 v117, v134
	v_exp_f32_e32 v134, v118
	v_exp_f32_e32 v118, v135
	v_exp_f32_e32 v135, v136
	v_exp_f32_e32 v136, v120
	v_exp_f32_e32 v120, v137
	v_exp_f32_e32 v137, v121
	v_exp_f32_e32 v121, v138
	v_exp_f32_e32 v138, v122
	v_exp_f32_e32 v122, v139
	v_exp_f32_e32 v139, v123
	v_exp_f32_e32 v123, v140
	v_exp_f32_e32 v140, v124
	v_exp_f32_e32 v217, v125
	v_cvt_pk_bf16_f32 v124, v128, v129
	v_cvt_pk_bf16_f32 v125, v130, v131
	s_mov_b32 s89, s88
	v_mov_b64_e32 v[130:131], s[90:91]
	v_exp_f32_e32 v132, v132
	v_mov_b64_e32 v[128:129], s[88:89]
	v_exp_f32_e32 v222, v126
	v_exp_f32_e32 v223, v127
	v_cvt_pk_bf16_f32 v126, v132, v116
	v_cvt_pk_bf16_f32 v127, v117, v118
	v_exp_f32_e32 v141, v141
	v_exp_f32_e32 v142, v142
	v_mfma_f32_32x32x16_bf16 v[16:31], v[128:131], v[124:127], v[16:31]
	v_exp_f32_e32 v143, v143
	v_cvt_pk_bf16_f32 v120, v135, v120
	v_cvt_pk_bf16_f32 v121, v121, v122
	v_cvt_pk_bf16_f32 v122, v123, v141
	v_cvt_pk_bf16_f32 v123, v142, v143
	v_exp_f32_e32 v112, v112
	v_exp_f32_e32 v113, v113
	v_mfma_f32_32x32x16_bf16 v[16:31], v[128:131], v[120:123], v[16:31]
	v_exp_f32_e32 v114, v114
	v_exp_f32_e32 v115, v115
	v_exp_f32_e32 v119, v119
	v_cvt_pk_bf16_f32 v116, v112, v113
	v_cvt_pk_bf16_f32 v118, v216, v133
	v_cvt_pk_bf16_f32 v117, v114, v115
	v_cvt_pk_bf16_f32 v119, v134, v119
	v_cvt_pk_bf16_f32 v112, v136, v137
	v_cvt_pk_bf16_f32 v113, v138, v139
	v_mfma_f32_32x32x16_bf16 v[16:31], v[128:131], v[116:119], v[16:31]
	v_cvt_pk_bf16_f32 v114, v140, v217
	v_cvt_pk_bf16_f32 v115, v222, v223
	s_waitcnt lgkmcnt(0)
	s_nop 1
	v_mfma_f32_32x32x16_bf16 v[16:31], v[128:131], v[112:115], v[16:31]
	v_mfma_f32_32x32x16_bf16 v[80:95], v[208:211], v[124:127], v[80:95]
	v_mfma_f32_32x32x16_bf16 v[80:95], v[10:13], v[120:123], v[80:95]
	v_mfma_f32_32x32x16_bf16 v[80:95], v[6:9], v[116:119], v[80:95]
	v_mfma_f32_32x32x16_bf16 v[80:95], v[2:5], v[112:115], v[80:95]
	ds_read_b64_tr_b16 v[2:3], v241 offset:64
	ds_read_b64_tr_b16 v[4:5], v241 offset:2624
	ds_read_b64_tr_b16 v[6:7], v241 offset:5184
	ds_read_b64_tr_b16 v[8:9], v241 offset:7744
	ds_read_b64_tr_b16 v[10:11], v241 offset:10304
	ds_read_b64_tr_b16 v[12:13], v241 offset:12864
	ds_read_b64_tr_b16 v[128:129], v241 offset:15424
	ds_read_b64_tr_b16 v[130:131], v241 offset:17984
	s_waitcnt lgkmcnt(6)
	s_nop 0
	s_nop 0
	v_mfma_f32_32x32x16_bf16 v[64:79], v[2:5], v[124:127], v[64:79]
	s_waitcnt lgkmcnt(4)
	v_mfma_f32_32x32x16_bf16 v[64:79], v[6:9], v[120:123], v[64:79]
	s_waitcnt lgkmcnt(2)
	v_mfma_f32_32x32x16_bf16 v[64:79], v[10:13], v[116:119], v[64:79]
	s_waitcnt lgkmcnt(0)
	v_mfma_f32_32x32x16_bf16 v[64:79], v[128:131], v[112:115], v[64:79]
	ds_read_b64_tr_b16 v[2:3], v241 offset:128
	ds_read_b64_tr_b16 v[4:5], v241 offset:2688
	ds_read_b64_tr_b16 v[6:7], v241 offset:5248
	ds_read_b64_tr_b16 v[8:9], v241 offset:7808
	ds_read_b64_tr_b16 v[10:11], v241 offset:10368
	ds_read_b64_tr_b16 v[12:13], v241 offset:12928
	ds_read_b64_tr_b16 v[128:129], v241 offset:15488
	ds_read_b64_tr_b16 v[130:131], v241 offset:18048
	s_waitcnt lgkmcnt(6)
	s_nop 0
	s_nop 0
	v_mfma_f32_32x32x16_bf16 v[48:63], v[2:5], v[124:127], v[48:63]
	s_waitcnt lgkmcnt(4)
	v_mfma_f32_32x32x16_bf16 v[48:63], v[6:9], v[120:123], v[48:63]
	s_waitcnt lgkmcnt(2)
	v_mfma_f32_32x32x16_bf16 v[48:63], v[10:13], v[116:119], v[48:63]
	s_waitcnt lgkmcnt(0)
	v_mfma_f32_32x32x16_bf16 v[48:63], v[128:131], v[112:115], v[48:63]
	ds_read_b64_tr_b16 v[2:3], v241 offset:192
	ds_read_b64_tr_b16 v[4:5], v241 offset:2752
	ds_read_b64_tr_b16 v[6:7], v241 offset:5312
	ds_read_b64_tr_b16 v[8:9], v241 offset:7872
	ds_read_b64_tr_b16 v[10:11], v241 offset:10432
	ds_read_b64_tr_b16 v[12:13], v241 offset:12992
	ds_read_b64_tr_b16 v[128:129], v241 offset:15552
	ds_read_b64_tr_b16 v[130:131], v241 offset:18112
	s_waitcnt lgkmcnt(6)
	s_nop 0
	s_nop 0
	v_mfma_f32_32x32x16_bf16 v[32:47], v[2:5], v[124:127], v[32:47]
	s_waitcnt lgkmcnt(4)
	v_mfma_f32_32x32x16_bf16 v[32:47], v[6:9], v[120:123], v[32:47]
	s_waitcnt lgkmcnt(2)
	v_mfma_f32_32x32x16_bf16 v[32:47], v[10:13], v[116:119], v[32:47]
	s_waitcnt lgkmcnt(0)
	v_mfma_f32_32x32x16_bf16 v[32:47], v[128:131], v[112:115], v[32:47]
	s_mov_b64 s[56:57], 0
	s_andn2_b64 vcc, exec, s[54:55]
	s_cbranch_vccnz .LBB0_300

; __device__ __forceinline__ int crow(int i, int h) { return (i & 3) + 8 * (i >> 2) + 4 * h; }
; template <int DQK, int DV, int MODE>
; __device__ __forceinline__ void attn_item(LAS unsigned char* lds, int item, const AttnCtx& cx) {
;     ...
;     auto do_qk = [&](int j, bool vpre) {
;         const unsigned kaddr = (unsigned)(size_t)(lds + (j % NST) * SB + koff) + r * KP + 16 * h;
;         const unsigned va = vaddr_of(j);
;         bf16x8 kfr[1][4];
;         K_ISSUE(0, 0);
; #pragma unroll
;         for (int kb = 0; kb < NQF / 2; ++kb) {
;             LGKM0(); SBAR();
;             if (kb == 0) { if (MODE == 1) { s0 = MFMA32(kfr[0][0], qf[0], cin0); s1 = MFMA32(kfr[0][1], qf[0], cin1); } else { s0 = MFMA32(kfr[0][0], qf[0], negm); s1 = MFMA32(kfr[0][1], qf[0], negm); } }
;             else { s0 = MFMA32(kfr[0][0], qf[2 * kb], s0); s1 = MFMA32(kfr[0][1], qf[2 * kb], s1); }
;             s0 = MFMA32(kfr[0][2], qf[2 * kb + 1], s0); s1 = MFMA32(kfr[0][3], qf[2 * kb + 1], s1);
;             SBAR();
;             if (kb + 1 < NQF / 2) K_ISSUE(0, kb + 1); else if (vpre) V_ISSUE(va, 0, 0);
;         }
;     };
;     auto do_soft = [&](int j) {
;         if (MODE == 1) {
;             const int rk = na_rs0 + j; const int bbase = (rk - na_rq + 7) * 31 + 15 - na_cq + 64;
; #pragma unroll
;             for (int i = 0; i < 16; ++i) { s0[i] += biasL[bbase + crow(i, h)]; s1[i] += biasL[bbase + crow(i, h) + 32]; }
;         }
;         if (MODE == 2) {
;             const int lk0 = c_l0 - 64 + 64 * j;
; #pragma unroll
;             for (int i = 0; i < 16; ++i) {
;                 const int lka = lk0 + crow(i, h), lkb = lka + 32;
;                 const bool v0 = (lka >= 0) && (lka < c_L) && (abs(lka - c_lq) <= 64), v1 = (lkb >= 0) && (lkb < c_L) && (abs(lkb - c_lq) <= 64);
;                 s0[i] = v0 ? s0[i] : NEGBIG; s1[i] = v1 ? s1[i] : NEGBIG;
;             }
;         }
;         float mx = max3f(s0[0], s1[0], s0[1]);
;         mx = max3f(mx, s1[1], s0[2]);
; #pragma unroll
;         for (int i = 2; i < 15; ++i) mx = max3f(mx, s1[i], s0[i + 1]);
;         mx = fmaxf(mx, s1[15]);
;         { auto rr = __builtin_amdgcn_permlane32_swap(__float_as_uint(mx), __float_as_uint(mx), false, false); mx = max3f(__uint_as_float(rr[0]), __uint_as_float(rr[1]), __uint_as_float(rr[0])); }
;         if (first || __builtin_amdgcn_ballot_w64(mx > THR) != 0ull) {
.LBB0_338:
	s_add_i32 s51, s51, 8
	s_cmp_lt_u32 s51, s37
	s_cselect_b64 s[0:1], -1, 0
	s_cmp_ge_u32 s50, s37
	s_cselect_b64 s[36:37], -1, 0
	s_or_b64 s[0:1], s[0:1], s[36:37]
	s_and_b64 vcc, exec, s[0:1]
	s_cbranch_vccnz .LBB0_323
	v_add_u32_e32 v66, s23, v204
	ds_read_b128 v[50:53], v66 offset:0
	ds_read_b128 v[54:57], v66 offset:4608
	ds_read_b128 v[58:61], v66 offset:32
	ds_read_b128 v[62:65], v66 offset:4640
	s_waitcnt lgkmcnt(0)
	s_add_i32 s0, s23, 0x2400
	s_xor_b64 s[40:41], s[38:39], -1
	v_add_u32_e32 v0, s0, v207
	v_mfma_f32_32x32x16_bf16 v[98:113], v[50:53], v[158:161], v[98:113]
	v_mfma_f32_32x32x16_bf16 v[82:97], v[54:57], v[158:161], v[82:97]
	v_mfma_f32_32x32x16_bf16 v[98:113], v[58:61], v[154:157], v[98:113]
	v_mfma_f32_32x32x16_bf16 v[82:97], v[62:65], v[154:157], v[82:97]
	ds_read_b128 v[50:53], v66 offset:64
	ds_read_b128 v[54:57], v66 offset:4672
	ds_read_b128 v[58:61], v66 offset:96
	ds_read_b128 v[62:65], v66 offset:4704
	s_waitcnt lgkmcnt(3)
	s_nop 0
	s_nop 0
	v_mfma_f32_32x32x16_bf16 v[98:113], v[50:53], v[150:153], v[98:113]
	s_waitcnt lgkmcnt(2)
	v_mfma_f32_32x32x16_bf16 v[82:97], v[54:57], v[150:153], v[82:97]
	s_waitcnt lgkmcnt(1)
	v_mfma_f32_32x32x16_bf16 v[98:113], v[58:61], v[146:149], v[98:113]
	s_waitcnt lgkmcnt(0)
	v_mfma_f32_32x32x16_bf16 v[82:97], v[62:65], v[146:149], v[82:97]
	ds_read_b64_tr_b16 v[62:63], v0 offset:0
	ds_read_b64_tr_b16 v[64:65], v0 offset:1536
	ds_read_b64_tr_b16 v[58:59], v0 offset:3072
	s_sub_i32 s0, s51, s31
	ds_read_b64_tr_b16 v[60:61], v0 offset:4608
	s_mul_i32 s0, s0, 31
	ds_read_b64_tr_b16 v[54:55], v0 offset:6144
	v_sub_u32_e32 v66, s0, v201
	ds_read_b64_tr_b16 v[56:57], v0 offset:7680
	v_lshlrev_b32_e32 v66, 2, v66
	ds_read_b64_tr_b16 v[50:51], v0 offset:9216
	v_add3_u32 v114, s3, v66, v194
	ds_read_b64_tr_b16 v[52:53], v0 offset:10752
	v_add_u32_e32 v66, 0x4a0, v114
	v_add_u32_e32 v68, 0x520, v114
	v_add_u32_e32 v70, 0x4a8, v114
	v_add_u32_e32 v72, 0x528, v114
	v_add_u32_e32 v74, 0x4c0, v114
	v_add_u32_e32 v76, 0x540, v114
	v_add_u32_e32 v78, 0x4c8, v114
	v_add_u32_e32 v80, 0x548, v114
	ds_read2_b32 v[66:67], v66 offset1:1
	ds_read2_b32 v[68:69], v68 offset1:1
	ds_read2_b32 v[70:71], v70 offset1:1
	ds_read2_b32 v[72:73], v72 offset1:1
	ds_read2_b32 v[74:75], v74 offset1:1
	ds_read2_b32 v[76:77], v76 offset1:1
	ds_read2_b32 v[78:79], v78 offset1:1
	ds_read2_b32 v[80:81], v80 offset1:1
	s_waitcnt lgkmcnt(6)
	v_pk_add_f32 v[68:69], v[82:83], v[68:69]
	s_waitcnt lgkmcnt(4)
	v_pk_add_f32 v[72:73], v[84:85], v[72:73]
	s_waitcnt lgkmcnt(2)
	v_pk_add_f32 v[76:77], v[86:87], v[76:77]
	v_add_u32_e32 v82, 0x4e0, v114
	s_waitcnt lgkmcnt(0)
	v_pk_add_f32 v[80:81], v[88:89], v[80:81]
	v_add_u32_e32 v84, 0x560, v114
	v_add_u32_e32 v86, 0x4e8, v114
	v_add_u32_e32 v88, 0x568, v114
	ds_read2_b32 v[82:83], v82 offset1:1
	ds_read2_b32 v[84:85], v84 offset1:1
	ds_read2_b32 v[86:87], v86 offset1:1
	ds_read2_b32 v[88:89], v88 offset1:1
	v_pk_add_f32 v[66:67], v[98:99], v[66:67]
	v_add_u32_e32 v98, 0x588, v114
	s_waitcnt lgkmcnt(2)
	v_pk_add_f32 v[84:85], v[90:91], v[84:85]
	v_add_u32_e32 v90, 0x500, v114
	s_waitcnt lgkmcnt(0)
	v_pk_add_f32 v[88:89], v[92:93], v[88:89]
	v_add_u32_e32 v92, 0x580, v114
	ds_read2_b32 v[90:91], v90 offset1:1
	ds_read2_b32 v[92:93], v92 offset1:1
	ds_read2_b32 v[98:99], v98 offset1:1
	v_pk_add_f32 v[70:71], v[100:101], v[70:71]
	v_pk_add_f32 v[74:75], v[102:103], v[74:75]
	v_pk_add_f32 v[78:79], v[104:105], v[78:79]
	v_pk_add_f32 v[82:83], v[106:107], v[82:83]
	s_waitcnt lgkmcnt(0)
	v_pk_add_f32 v[96:97], v[96:97], v[98:99]
	v_max3_f32 v98, v66, v68, v67
	v_pk_add_f32 v[92:93], v[94:95], v[92:93]
	v_max3_f32 v98, v98, v69, v70
	v_add_u32_e32 v94, 0x508, v114
	v_max3_f32 v98, v98, v72, v71
	ds_read2_b32 v[94:95], v94 offset1:1
	v_max3_f32 v98, v98, v73, v74
	v_pk_add_f32 v[86:87], v[108:109], v[86:87]
	v_max3_f32 v98, v98, v76, v75
	v_pk_add_f32 v[90:91], v[110:111], v[90:91]
	v_max3_f32 v98, v98, v77, v78
	s_waitcnt lgkmcnt(0)
	v_pk_add_f32 v[94:95], v[112:113], v[94:95]
	v_max3_f32 v98, v98, v80, v79
	s_andn2_b64 vcc, exec, s[40:41]
	v_max3_f32 v98, v98, v81, v82
	s_nop 0
	v_max3_f32 v98, v98, v84, v83
	s_nop 0
	v_max3_f32 v98, v98, v85, v86
	s_nop 0
	v_max3_f32 v98, v98, v88, v87
	s_nop 0
	v_max3_f32 v98, v98, v89, v90
	s_nop 0
	v_max3_f32 v98, v98, v92, v91
	s_nop 0
	v_max3_f32 v98, v98, v93, v94
	s_nop 0
	v_max3_f32 v98, v98, v96, v95
	s_nop 0
	v_max_f32_e32 v98, v98, v98
	v_max_f32_e32 v98, v98, v97
	v_mov_b32_e32 v99, v98
	s_nop 1
	v_permlane32_swap_b32_e32 v98, v99
	v_max3_f32 v98, v98, v99, v98
	v_cndmask_b32_e64 v99, 0, 1, s[40:41]
	v_cmp_ne_u32_e64 s[0:1], 1, v99
	s_mov_b64 s[40:41], s[38:39]
	s_cbranch_vccnz .LBB0_341
	v_cmp_lt_f32_e32 vcc, s29, v98
	s_cmp_lg_u64 vcc, 0
	s_cselect_b64 s[40:41], -1, 0
